# WS2: streaming waves 4-7 use a hand-written double-buffered x->fp16 loop (2 stages of 4 rows in flight, 4 row-sum butterflies interleaved), R0=40960 rows in phase 0
# speedup vs baseline: 1.0001x; 1.0001x over previous
; __device__ void p0_xconv(const Args& a) {
;     f16* XH = (f16*)(a.ws + WS_XH); float* SS = (float*)(a.ws + WS_SS);
;     int tid_ = threadIdx.x; asm volatile("" : "+v"(tid_));
;     const int lane = tid_ & 63, wv = tid_ >> 6;
;     const int nwv = (int)gridDim.x * 8;
;     for (int row0 = (int)blockIdx.x * 8 + wv; row0 < MROWS; row0 += 4 * nwv) {
;         f32x4 v[4][4];
; #pragma unroll
;         for (int r = 0; r < 4; ++r) {
;             const int row = row0 + r * nwv;
;             if (row < MROWS) {
;                 const float* src = (row < ROWS_PROMPT) ? a.x_prompt + (size_t)row * DM : a.x_sample + (size_t)(row - ROWS_PROMPT) * DM;
; #pragma unroll
;                 for (int i = 0; i < 4; ++i) v[r][i] = __builtin_nontemporal_load((const f32x4*)(src + i * 256 + lane * 4));
;             }
;         }
; #pragma unroll
;         for (int r = 0; r < 4; ++r) {
;             const int row = row0 + r * nwv;
;             if (row < MROWS) {
;                 float ss = 0.f;
; #pragma unroll
;                 for (int i = 0; i < 4; ++i) {
;                     const f32x4 x = v[r][i];
;                     ss += (x[0] * x[0] + x[1] * x[1]) + (x[2] * x[2] + x[3] * x[3]);
;                     f16x4 h; h[0] = (f16)x[0]; h[1] = (f16)x[1]; h[2] = (f16)x[2]; h[3] = (f16)x[3];
;                     *(f16x4*)(XH + (size_t)row * DM + i * 256 + lane * 4) = h;
;                 }
.Lws_x:
	v_and_b32_e32 v136, 63, v0
	v_lshrrev_b32_e32 v137, 6, v0
	s_nop 0
	v_readfirstlane_b32 s3, v137
	s_nop 3
	s_lshl_b32 s4, s2, 2
	s_add_i32 s3, s3, s4
	s_add_i32 s3, s3, -4
	s_mov_b64 s[12:13], 1
	v_xor_b32_e32 v130, 1, v136
	v_lshlrev_b32_e32 v130, 2, v130
	v_xor_b32_e32 v131, 2, v136
	v_lshlrev_b32_e32 v131, 2, v131
	v_xor_b32_e32 v132, 4, v136
	v_lshlrev_b32_e32 v132, 2, v132
	v_xor_b32_e32 v133, 8, v136
	v_lshlrev_b32_e32 v133, 2, v133
	v_xor_b32_e32 v134, 16, v136
	v_lshlrev_b32_e32 v134, 2, v134
	v_xor_b32_e32 v135, 32, v136
	v_lshlrev_b32_e32 v135, 2, v135
	v_lshlrev_b32_e32 v140, 4, v136
	v_lshlrev_b32_e32 v144, 3, v136
	v_lshlrev_b32_e32 v186, 2, v136
	v_lshlrev_b32_e32 v141, 4, v136
	v_add_u32_e32 v141, 0x400000, v141
	v_lshlrev_b32_e32 v145, 3, v136
	v_add_u32_e32 v145, 0x200000, v145
	v_lshlrev_b32_e32 v187, 2, v136
	v_add_u32_e32 v187, 0x10000, v187
	v_lshlrev_b32_e32 v142, 4, v136
	v_add_u32_e32 v142, 0x800000, v142
	v_lshlrev_b32_e32 v146, 3, v136
	v_add_u32_e32 v146, 0x400000, v146
	v_lshlrev_b32_e32 v188, 2, v136
	v_add_u32_e32 v188, 0x20000, v188
	v_lshlrev_b32_e32 v143, 4, v136
	v_add_u32_e32 v143, 0xc00000, v143
	v_lshlrev_b32_e32 v147, 3, v136
	v_add_u32_e32 v147, 0x600000, v147
	v_lshlrev_b32_e32 v189, 2, v136
	v_add_u32_e32 v189, 0x30000, v189
	s_add_i32 s6, s3, 0x0
	s_lshl_b32 s6, s6, 12
	s_add_u32 s4, s16, s6
	s_addc_u32 s5, s17, 0
	global_load_dwordx4 v[2:5], v140, s[4:5] nt
	global_load_dwordx4 v[6:9], v140, s[4:5] offset:1024 nt
	global_load_dwordx4 v[10:13], v140, s[4:5] offset:2048 nt
	global_load_dwordx4 v[14:17], v140, s[4:5] offset:3072 nt
	global_load_dwordx4 v[18:21], v141, s[4:5] nt
	global_load_dwordx4 v[22:25], v141, s[4:5] offset:1024 nt
	global_load_dwordx4 v[26:29], v141, s[4:5] offset:2048 nt
	global_load_dwordx4 v[30:33], v141, s[4:5] offset:3072 nt
	global_load_dwordx4 v[34:37], v142, s[4:5] nt
	global_load_dwordx4 v[38:41], v142, s[4:5] offset:1024 nt
	global_load_dwordx4 v[42:45], v142, s[4:5] offset:2048 nt
	global_load_dwordx4 v[46:49], v142, s[4:5] offset:3072 nt
	global_load_dwordx4 v[50:53], v143, s[4:5] nt
	global_load_dwordx4 v[54:57], v143, s[4:5] offset:1024 nt
	global_load_dwordx4 v[58:61], v143, s[4:5] offset:2048 nt
	global_load_dwordx4 v[62:65], v143, s[4:5] offset:3072 nt
	s_add_i32 s6, s3, 0x1000
	s_lshl_b32 s6, s6, 12
	s_add_u32 s4, s16, s6
	s_addc_u32 s5, s17, 0
	global_load_dwordx4 v[66:69], v140, s[4:5] nt
	global_load_dwordx4 v[70:73], v140, s[4:5] offset:1024 nt
	global_load_dwordx4 v[74:77], v140, s[4:5] offset:2048 nt
	global_load_dwordx4 v[78:81], v140, s[4:5] offset:3072 nt
	global_load_dwordx4 v[82:85], v141, s[4:5] nt
	global_load_dwordx4 v[86:89], v141, s[4:5] offset:1024 nt
	global_load_dwordx4 v[90:93], v141, s[4:5] offset:2048 nt
	global_load_dwordx4 v[94:97], v141, s[4:5] offset:3072 nt
	global_load_dwordx4 v[98:101], v142, s[4:5] nt
	global_load_dwordx4 v[102:105], v142, s[4:5] offset:1024 nt
	global_load_dwordx4 v[106:109], v142, s[4:5] offset:2048 nt
	global_load_dwordx4 v[110:113], v142, s[4:5] offset:3072 nt
	global_load_dwordx4 v[114:117], v143, s[4:5] nt
	global_load_dwordx4 v[118:121], v143, s[4:5] offset:1024 nt
	global_load_dwordx4 v[122:125], v143, s[4:5] offset:2048 nt
	global_load_dwordx4 v[126:129], v143, s[4:5] offset:3072 nt
	s_waitcnt vmcnt(16)
	s_add_i32 s6, s3, 0x0
	s_lshl_b32 s7, s6, 11
	s_add_u32 s10, s40, s7
	s_addc_u32 s11, s41, 0
	s_lshl_b32 s7, s6, 6
	s_add_u32 s6, s40, s7
	s_addc_u32 s7, s41, 0
	s_add_u32 s6, s6, 0x1f800000
	s_addc_u32 s7, s7, 0
	v_mul_f32_e32 v150, v3, v3
	v_mul_f32_e32 v151, v5, v5
	v_fmac_f32_e32 v150, v2, v2
	v_fmac_f32_e32 v151, v4, v4
	v_add_f32_e32 v160, v150, v151
	v_cvt_pk_f16_f32 v170, v2, v3
	v_cvt_pk_f16_f32 v171, v4, v5
	v_mul_f32_e32 v150, v7, v7
	v_mul_f32_e32 v151, v9, v9
	v_fmac_f32_e32 v150, v6, v6
	v_fmac_f32_e32 v151, v8, v8
	v_add_f32_e32 v152, v150, v151
	v_add_f32_e32 v160, v160, v152
	v_cvt_pk_f16_f32 v172, v6, v7
	v_cvt_pk_f16_f32 v173, v8, v9
	v_mul_f32_e32 v150, v11, v11
	v_mul_f32_e32 v151, v13, v13
	v_fmac_f32_e32 v150, v10, v10
	v_fmac_f32_e32 v151, v12, v12
	v_add_f32_e32 v152, v150, v151
	v_add_f32_e32 v160, v160, v152
	v_cvt_pk_f16_f32 v174, v10, v11
	v_cvt_pk_f16_f32 v175, v12, v13
	v_mul_f32_e32 v150, v15, v15
	v_mul_f32_e32 v151, v17, v17
	v_fmac_f32_e32 v150, v14, v14
	v_fmac_f32_e32 v151, v16, v16
	v_add_f32_e32 v152, v150, v151
	v_add_f32_e32 v160, v160, v152
	v_cvt_pk_f16_f32 v176, v14, v15
	v_cvt_pk_f16_f32 v177, v16, v17
	global_store_dwordx2 v144, v[170:171], s[10:11]
	global_store_dwordx2 v144, v[172:173], s[10:11] offset:512
	global_store_dwordx2 v144, v[174:175], s[10:11] offset:1024
	global_store_dwordx2 v144, v[176:177], s[10:11] offset:1536
	v_mul_f32_e32 v150, v19, v19
	v_mul_f32_e32 v151, v21, v21
	v_fmac_f32_e32 v150, v18, v18
	v_fmac_f32_e32 v151, v20, v20
	v_add_f32_e32 v161, v150, v151
	v_cvt_pk_f16_f32 v178, v18, v19
	v_cvt_pk_f16_f32 v179, v20, v21
	v_mul_f32_e32 v150, v23, v23
	v_mul_f32_e32 v151, v25, v25
	v_fmac_f32_e32 v150, v22, v22
	v_fmac_f32_e32 v151, v24, v24
	v_add_f32_e32 v152, v150, v151
	v_add_f32_e32 v161, v161, v152
	v_cvt_pk_f16_f32 v180, v22, v23
	v_cvt_pk_f16_f32 v181, v24, v25
	v_mul_f32_e32 v150, v27, v27
	v_mul_f32_e32 v151, v29, v29
	v_fmac_f32_e32 v150, v26, v26
	v_fmac_f32_e32 v151, v28, v28
	v_add_f32_e32 v152, v150, v151
	v_add_f32_e32 v161, v161, v152
	v_cvt_pk_f16_f32 v182, v26, v27
	v_cvt_pk_f16_f32 v183, v28, v29
	v_mul_f32_e32 v150, v31, v31
	v_mul_f32_e32 v151, v33, v33
	v_fmac_f32_e32 v150, v30, v30
	v_fmac_f32_e32 v151, v32, v32
	v_add_f32_e32 v152, v150, v151
	v_add_f32_e32 v161, v161, v152
	v_cvt_pk_f16_f32 v184, v30, v31
; __device__ void p0_xconv(const Args& a) {
;     ...
;                 for (int i = 0; i < 4; ++i) {
;                     const f32x4 x = v[r][i];
;                     ss += (x[0] * x[0] + x[1] * x[1]) + (x[2] * x[2] + x[3] * x[3]);
;                     f16x4 h; h[0] = (f16)x[0]; h[1] = (f16)x[1]; h[2] = (f16)x[2]; h[3] = (f16)x[3];
;                     *(f16x4*)(XH + (size_t)row * DM + i * 256 + lane * 4) = h;
;                 }
; #pragma unroll
;                 for (int o = 1; o < 64; o <<= 1) ss += __shfl_xor(ss, o);
;                 if (lane < 16) SS[(size_t)row * 16 + lane] = (lane == 0) ? ss : 0.f;
	v_cvt_pk_f16_f32 v185, v32, v33
	global_store_dwordx2 v145, v[178:179], s[10:11]
	global_store_dwordx2 v145, v[180:181], s[10:11] offset:512
	global_store_dwordx2 v145, v[182:183], s[10:11] offset:1024
	global_store_dwordx2 v145, v[184:185], s[10:11] offset:1536
	v_mul_f32_e32 v150, v35, v35
	v_mul_f32_e32 v151, v37, v37
	v_fmac_f32_e32 v150, v34, v34
	v_fmac_f32_e32 v151, v36, v36
	v_add_f32_e32 v162, v150, v151
	v_cvt_pk_f16_f32 v170, v34, v35
	v_cvt_pk_f16_f32 v171, v36, v37
	v_mul_f32_e32 v150, v39, v39
	v_mul_f32_e32 v151, v41, v41
	v_fmac_f32_e32 v150, v38, v38
	v_fmac_f32_e32 v151, v40, v40
	v_add_f32_e32 v152, v150, v151
	v_add_f32_e32 v162, v162, v152
	v_cvt_pk_f16_f32 v172, v38, v39
	v_cvt_pk_f16_f32 v173, v40, v41
	v_mul_f32_e32 v150, v43, v43
	v_mul_f32_e32 v151, v45, v45
	v_fmac_f32_e32 v150, v42, v42
	v_fmac_f32_e32 v151, v44, v44
	v_add_f32_e32 v152, v150, v151
	v_add_f32_e32 v162, v162, v152
	v_cvt_pk_f16_f32 v174, v42, v43
	v_cvt_pk_f16_f32 v175, v44, v45
	v_mul_f32_e32 v150, v47, v47
	v_mul_f32_e32 v151, v49, v49
	v_fmac_f32_e32 v150, v46, v46
	v_fmac_f32_e32 v151, v48, v48
	v_add_f32_e32 v152, v150, v151
	v_add_f32_e32 v162, v162, v152
	v_cvt_pk_f16_f32 v176, v46, v47
	v_cvt_pk_f16_f32 v177, v48, v49
	global_store_dwordx2 v146, v[170:171], s[10:11]
	global_store_dwordx2 v146, v[172:173], s[10:11] offset:512
	global_store_dwordx2 v146, v[174:175], s[10:11] offset:1024
	global_store_dwordx2 v146, v[176:177], s[10:11] offset:1536
	v_mul_f32_e32 v150, v51, v51
	v_mul_f32_e32 v151, v53, v53
	v_fmac_f32_e32 v150, v50, v50
	v_fmac_f32_e32 v151, v52, v52
	v_add_f32_e32 v163, v150, v151
	v_cvt_pk_f16_f32 v178, v50, v51
	v_cvt_pk_f16_f32 v179, v52, v53
	v_mul_f32_e32 v150, v55, v55
	v_mul_f32_e32 v151, v57, v57
	v_fmac_f32_e32 v150, v54, v54
	v_fmac_f32_e32 v151, v56, v56
	v_add_f32_e32 v152, v150, v151
	v_add_f32_e32 v163, v163, v152
	v_cvt_pk_f16_f32 v180, v54, v55
	v_cvt_pk_f16_f32 v181, v56, v57
	v_mul_f32_e32 v150, v59, v59
	v_mul_f32_e32 v151, v61, v61
	v_fmac_f32_e32 v150, v58, v58
	v_fmac_f32_e32 v151, v60, v60
	v_add_f32_e32 v152, v150, v151
	v_add_f32_e32 v163, v163, v152
	v_cvt_pk_f16_f32 v182, v58, v59
	v_cvt_pk_f16_f32 v183, v60, v61
	v_mul_f32_e32 v150, v63, v63
	v_mul_f32_e32 v151, v65, v65
	v_fmac_f32_e32 v150, v62, v62
	v_fmac_f32_e32 v151, v64, v64
	v_add_f32_e32 v152, v150, v151
	v_add_f32_e32 v163, v163, v152
	v_cvt_pk_f16_f32 v184, v62, v63
	v_cvt_pk_f16_f32 v185, v64, v65
	global_store_dwordx2 v147, v[178:179], s[10:11]
	global_store_dwordx2 v147, v[180:181], s[10:11] offset:512
	global_store_dwordx2 v147, v[182:183], s[10:11] offset:1024
	global_store_dwordx2 v147, v[184:185], s[10:11] offset:1536
	ds_bpermute_b32 v164, v130, v160
	ds_bpermute_b32 v165, v130, v161
	ds_bpermute_b32 v166, v130, v162
	ds_bpermute_b32 v167, v130, v163
	s_waitcnt lgkmcnt(0)
	v_add_f32_e32 v160, v160, v164
	v_add_f32_e32 v161, v161, v165
	v_add_f32_e32 v162, v162, v166
	v_add_f32_e32 v163, v163, v167
	ds_bpermute_b32 v164, v131, v160
	ds_bpermute_b32 v165, v131, v161
	ds_bpermute_b32 v166, v131, v162
	ds_bpermute_b32 v167, v131, v163
	s_waitcnt lgkmcnt(0)
	v_add_f32_e32 v160, v160, v164
	v_add_f32_e32 v161, v161, v165
	v_add_f32_e32 v162, v162, v166
	v_add_f32_e32 v163, v163, v167
	ds_bpermute_b32 v164, v132, v160
	ds_bpermute_b32 v165, v132, v161
	ds_bpermute_b32 v166, v132, v162
	ds_bpermute_b32 v167, v132, v163
	s_waitcnt lgkmcnt(0)
	v_add_f32_e32 v160, v160, v164
	v_add_f32_e32 v161, v161, v165
	v_add_f32_e32 v162, v162, v166
	v_add_f32_e32 v163, v163, v167
	ds_bpermute_b32 v164, v133, v160
	ds_bpermute_b32 v165, v133, v161
	ds_bpermute_b32 v166, v133, v162
	ds_bpermute_b32 v167, v133, v163
	s_waitcnt lgkmcnt(0)
	v_add_f32_e32 v160, v160, v164
	v_add_f32_e32 v161, v161, v165
	v_add_f32_e32 v162, v162, v166
	v_add_f32_e32 v163, v163, v167
	ds_bpermute_b32 v164, v134, v160
	ds_bpermute_b32 v165, v134, v161
	ds_bpermute_b32 v166, v134, v162
	ds_bpermute_b32 v167, v134, v163
	s_waitcnt lgkmcnt(0)
	v_add_f32_e32 v160, v160, v164
	v_add_f32_e32 v161, v161, v165
	v_add_f32_e32 v162, v162, v166
	v_add_f32_e32 v163, v163, v167
	ds_bpermute_b32 v164, v135, v160
	ds_bpermute_b32 v165, v135, v161
	ds_bpermute_b32 v166, v135, v162
	ds_bpermute_b32 v167, v135, v163
	s_waitcnt lgkmcnt(0)
	v_add_f32_e32 v160, v160, v164
	v_add_f32_e32 v161, v161, v165
	v_add_f32_e32 v162, v162, v166
	v_add_f32_e32 v163, v163, v167
	v_cndmask_b32_e64 v164, 0, v160, s[12:13]
	v_cndmask_b32_e64 v165, 0, v161, s[12:13]
	v_cndmask_b32_e64 v166, 0, v162, s[12:13]
	v_cndmask_b32_e64 v167, 0, v163, s[12:13]
	s_mov_b64 exec, 0xffff
	global_store_dword v186, v164, s[6:7]
	global_store_dword v187, v165, s[6:7]
	global_store_dword v188, v166, s[6:7]
	global_store_dword v189, v167, s[6:7]
	s_mov_b64 exec, -1
	s_add_i32 s6, s3, 0x2000
	s_lshl_b32 s6, s6, 12
	s_add_u32 s4, s16, s6
	s_addc_u32 s5, s17, 0
	global_load_dwordx4 v[2:5], v140, s[4:5] nt
	global_load_dwordx4 v[6:9], v140, s[4:5] offset:1024 nt
	global_load_dwordx4 v[10:13], v140, s[4:5] offset:2048 nt
	global_load_dwordx4 v[14:17], v140, s[4:5] offset:3072 nt
	global_load_dwordx4 v[18:21], v141, s[4:5] nt
	global_load_dwordx4 v[22:25], v141, s[4:5] offset:1024 nt
	global_load_dwordx4 v[26:29], v141, s[4:5] offset:2048 nt
	global_load_dwordx4 v[30:33], v141, s[4:5] offset:3072 nt
	global_load_dwordx4 v[34:37], v142, s[4:5] nt
	global_load_dwordx4 v[38:41], v142, s[4:5] offset:1024 nt
	global_load_dwordx4 v[42:45], v142, s[4:5] offset:2048 nt
	global_load_dwordx4 v[46:49], v142, s[4:5] offset:3072 nt
	global_load_dwordx4 v[50:53], v143, s[4:5] nt
	global_load_dwordx4 v[54:57], v143, s[4:5] offset:1024 nt
	global_load_dwordx4 v[58:61], v143, s[4:5] offset:2048 nt
	global_load_dwordx4 v[62:65], v143, s[4:5] offset:3072 nt
	s_waitcnt vmcnt(36)
; __device__ void p0_xconv(const Args& a) {
;     ...
; #pragma unroll
;         for (int r = 0; r < 4; ++r) {
;             const int row = row0 + r * nwv;
;             if (row < MROWS) {
;                 float ss = 0.f;
; #pragma unroll
;                 for (int i = 0; i < 4; ++i) {
;                     const f32x4 x = v[r][i];
;                     ss += (x[0] * x[0] + x[1] * x[1]) + (x[2] * x[2] + x[3] * x[3]);
;                     f16x4 h; h[0] = (f16)x[0]; h[1] = (f16)x[1]; h[2] = (f16)x[2]; h[3] = (f16)x[3];
;                     *(f16x4*)(XH + (size_t)row * DM + i * 256 + lane * 4) = h;
;                 }
; #pragma unroll
;                 for (int o = 1; o < 64; o <<= 1) ss += __shfl_xor(ss, o);
	s_add_i32 s6, s3, 0x1000
	s_lshl_b32 s7, s6, 11
	s_add_u32 s10, s40, s7
	s_addc_u32 s11, s41, 0
	s_lshl_b32 s7, s6, 6
	s_add_u32 s6, s40, s7
	s_addc_u32 s7, s41, 0
	s_add_u32 s6, s6, 0x1f800000
	s_addc_u32 s7, s7, 0
	v_mul_f32_e32 v150, v67, v67
	v_mul_f32_e32 v151, v69, v69
	v_fmac_f32_e32 v150, v66, v66
	v_fmac_f32_e32 v151, v68, v68
	v_add_f32_e32 v160, v150, v151
	v_cvt_pk_f16_f32 v170, v66, v67
	v_cvt_pk_f16_f32 v171, v68, v69
	v_mul_f32_e32 v150, v71, v71
	v_mul_f32_e32 v151, v73, v73
	v_fmac_f32_e32 v150, v70, v70
	v_fmac_f32_e32 v151, v72, v72
	v_add_f32_e32 v152, v150, v151
	v_add_f32_e32 v160, v160, v152
	v_cvt_pk_f16_f32 v172, v70, v71
	v_cvt_pk_f16_f32 v173, v72, v73
	v_mul_f32_e32 v150, v75, v75
	v_mul_f32_e32 v151, v77, v77
	v_fmac_f32_e32 v150, v74, v74
	v_fmac_f32_e32 v151, v76, v76
	v_add_f32_e32 v152, v150, v151
	v_add_f32_e32 v160, v160, v152
	v_cvt_pk_f16_f32 v174, v74, v75
	v_cvt_pk_f16_f32 v175, v76, v77
	v_mul_f32_e32 v150, v79, v79
	v_mul_f32_e32 v151, v81, v81
	v_fmac_f32_e32 v150, v78, v78
	v_fmac_f32_e32 v151, v80, v80
	v_add_f32_e32 v152, v150, v151
	v_add_f32_e32 v160, v160, v152
	v_cvt_pk_f16_f32 v176, v78, v79
	v_cvt_pk_f16_f32 v177, v80, v81
	global_store_dwordx2 v144, v[170:171], s[10:11]
	global_store_dwordx2 v144, v[172:173], s[10:11] offset:512
	global_store_dwordx2 v144, v[174:175], s[10:11] offset:1024
	global_store_dwordx2 v144, v[176:177], s[10:11] offset:1536
	v_mul_f32_e32 v150, v83, v83
	v_mul_f32_e32 v151, v85, v85
	v_fmac_f32_e32 v150, v82, v82
	v_fmac_f32_e32 v151, v84, v84
	v_add_f32_e32 v161, v150, v151
	v_cvt_pk_f16_f32 v178, v82, v83
	v_cvt_pk_f16_f32 v179, v84, v85
	v_mul_f32_e32 v150, v87, v87
	v_mul_f32_e32 v151, v89, v89
	v_fmac_f32_e32 v150, v86, v86
	v_fmac_f32_e32 v151, v88, v88
	v_add_f32_e32 v152, v150, v151
	v_add_f32_e32 v161, v161, v152
	v_cvt_pk_f16_f32 v180, v86, v87
	v_cvt_pk_f16_f32 v181, v88, v89
	v_mul_f32_e32 v150, v91, v91
	v_mul_f32_e32 v151, v93, v93
	v_fmac_f32_e32 v150, v90, v90
	v_fmac_f32_e32 v151, v92, v92
	v_add_f32_e32 v152, v150, v151
	v_add_f32_e32 v161, v161, v152
	v_cvt_pk_f16_f32 v182, v90, v91
	v_cvt_pk_f16_f32 v183, v92, v93
	v_mul_f32_e32 v150, v95, v95
	v_mul_f32_e32 v151, v97, v97
	v_fmac_f32_e32 v150, v94, v94
	v_fmac_f32_e32 v151, v96, v96
	v_add_f32_e32 v152, v150, v151
	v_add_f32_e32 v161, v161, v152
	v_cvt_pk_f16_f32 v184, v94, v95
	v_cvt_pk_f16_f32 v185, v96, v97
	global_store_dwordx2 v145, v[178:179], s[10:11]
	global_store_dwordx2 v145, v[180:181], s[10:11] offset:512
	global_store_dwordx2 v145, v[182:183], s[10:11] offset:1024
	global_store_dwordx2 v145, v[184:185], s[10:11] offset:1536
	v_mul_f32_e32 v150, v99, v99
	v_mul_f32_e32 v151, v101, v101
	v_fmac_f32_e32 v150, v98, v98
	v_fmac_f32_e32 v151, v100, v100
	v_add_f32_e32 v162, v150, v151
	v_cvt_pk_f16_f32 v170, v98, v99
	v_cvt_pk_f16_f32 v171, v100, v101
	v_mul_f32_e32 v150, v103, v103
	v_mul_f32_e32 v151, v105, v105
	v_fmac_f32_e32 v150, v102, v102
	v_fmac_f32_e32 v151, v104, v104
	v_add_f32_e32 v152, v150, v151
	v_add_f32_e32 v162, v162, v152
	v_cvt_pk_f16_f32 v172, v102, v103
	v_cvt_pk_f16_f32 v173, v104, v105
	v_mul_f32_e32 v150, v107, v107
	v_mul_f32_e32 v151, v109, v109
	v_fmac_f32_e32 v150, v106, v106
	v_fmac_f32_e32 v151, v108, v108
	v_add_f32_e32 v152, v150, v151
	v_add_f32_e32 v162, v162, v152
	v_cvt_pk_f16_f32 v174, v106, v107
	v_cvt_pk_f16_f32 v175, v108, v109
	v_mul_f32_e32 v150, v111, v111
	v_mul_f32_e32 v151, v113, v113
	v_fmac_f32_e32 v150, v110, v110
	v_fmac_f32_e32 v151, v112, v112
	v_add_f32_e32 v152, v150, v151
	v_add_f32_e32 v162, v162, v152
	v_cvt_pk_f16_f32 v176, v110, v111
	v_cvt_pk_f16_f32 v177, v112, v113
	global_store_dwordx2 v146, v[170:171], s[10:11]
	global_store_dwordx2 v146, v[172:173], s[10:11] offset:512
	global_store_dwordx2 v146, v[174:175], s[10:11] offset:1024
	global_store_dwordx2 v146, v[176:177], s[10:11] offset:1536
	v_mul_f32_e32 v150, v115, v115
	v_mul_f32_e32 v151, v117, v117
	v_fmac_f32_e32 v150, v114, v114
	v_fmac_f32_e32 v151, v116, v116
	v_add_f32_e32 v163, v150, v151
	v_cvt_pk_f16_f32 v178, v114, v115
	v_cvt_pk_f16_f32 v179, v116, v117
	v_mul_f32_e32 v150, v119, v119
	v_mul_f32_e32 v151, v121, v121
	v_fmac_f32_e32 v150, v118, v118
	v_fmac_f32_e32 v151, v120, v120
	v_add_f32_e32 v152, v150, v151
	v_add_f32_e32 v163, v163, v152
	v_cvt_pk_f16_f32 v180, v118, v119
	v_cvt_pk_f16_f32 v181, v120, v121
	v_mul_f32_e32 v150, v123, v123
	v_mul_f32_e32 v151, v125, v125
	v_fmac_f32_e32 v150, v122, v122
	v_fmac_f32_e32 v151, v124, v124
	v_add_f32_e32 v152, v150, v151
	v_add_f32_e32 v163, v163, v152
	v_cvt_pk_f16_f32 v182, v122, v123
	v_cvt_pk_f16_f32 v183, v124, v125
	v_mul_f32_e32 v150, v127, v127
	v_mul_f32_e32 v151, v129, v129
	v_fmac_f32_e32 v150, v126, v126
	v_fmac_f32_e32 v151, v128, v128
	v_add_f32_e32 v152, v150, v151
	v_add_f32_e32 v163, v163, v152
	v_cvt_pk_f16_f32 v184, v126, v127
	v_cvt_pk_f16_f32 v185, v128, v129
	global_store_dwordx2 v147, v[178:179], s[10:11]
	global_store_dwordx2 v147, v[180:181], s[10:11] offset:512
	global_store_dwordx2 v147, v[182:183], s[10:11] offset:1024
	global_store_dwordx2 v147, v[184:185], s[10:11] offset:1536
	ds_bpermute_b32 v164, v130, v160
	ds_bpermute_b32 v165, v130, v161
	ds_bpermute_b32 v166, v130, v162
	ds_bpermute_b32 v167, v130, v163
	s_waitcnt lgkmcnt(0)
	v_add_f32_e32 v160, v160, v164
	v_add_f32_e32 v161, v161, v165
	v_add_f32_e32 v162, v162, v166
	v_add_f32_e32 v163, v163, v167
	ds_bpermute_b32 v164, v131, v160
	ds_bpermute_b32 v165, v131, v161
	ds_bpermute_b32 v166, v131, v162
	ds_bpermute_b32 v167, v131, v163
	s_waitcnt lgkmcnt(0)
; __device__ void p0_xconv(const Args& a) {
;     ...
;     for (int row0 = (int)blockIdx.x * 8 + wv; row0 < MROWS; row0 += 4 * nwv) {
;         f32x4 v[4][4];
; #pragma unroll
;         for (int r = 0; r < 4; ++r) {
;             const int row = row0 + r * nwv;
;             if (row < MROWS) {
;                 const float* src = (row < ROWS_PROMPT) ? a.x_prompt + (size_t)row * DM : a.x_sample + (size_t)(row - ROWS_PROMPT) * DM;
; #pragma unroll
;                 for (int i = 0; i < 4; ++i) v[r][i] = __builtin_nontemporal_load((const f32x4*)(src + i * 256 + lane * 4));
;             }
;         }
; #pragma unroll
;         for (int r = 0; r < 4; ++r) {
;             const int row = row0 + r * nwv;
;             if (row < MROWS) {
;                 float ss = 0.f;
; #pragma unroll
;                 for (int i = 0; i < 4; ++i) {
;                     const f32x4 x = v[r][i];
;                     ss += (x[0] * x[0] + x[1] * x[1]) + (x[2] * x[2] + x[3] * x[3]);
;                     f16x4 h; h[0] = (f16)x[0]; h[1] = (f16)x[1]; h[2] = (f16)x[2]; h[3] = (f16)x[3];
;                     *(f16x4*)(XH + (size_t)row * DM + i * 256 + lane * 4) = h;
;                 }
; #pragma unroll
;                 for (int o = 1; o < 64; o <<= 1) ss += __shfl_xor(ss, o);
;                 if (lane < 16) SS[(size_t)row * 16 + lane] = (lane == 0) ? ss : 0.f;
	v_add_f32_e32 v160, v160, v164
	v_add_f32_e32 v161, v161, v165
	v_add_f32_e32 v162, v162, v166
	v_add_f32_e32 v163, v163, v167
	ds_bpermute_b32 v164, v132, v160
	ds_bpermute_b32 v165, v132, v161
	ds_bpermute_b32 v166, v132, v162
	ds_bpermute_b32 v167, v132, v163
	s_waitcnt lgkmcnt(0)
	v_add_f32_e32 v160, v160, v164
	v_add_f32_e32 v161, v161, v165
	v_add_f32_e32 v162, v162, v166
	v_add_f32_e32 v163, v163, v167
	ds_bpermute_b32 v164, v133, v160
	ds_bpermute_b32 v165, v133, v161
	ds_bpermute_b32 v166, v133, v162
	ds_bpermute_b32 v167, v133, v163
	s_waitcnt lgkmcnt(0)
	v_add_f32_e32 v160, v160, v164
	v_add_f32_e32 v161, v161, v165
	v_add_f32_e32 v162, v162, v166
	v_add_f32_e32 v163, v163, v167
	ds_bpermute_b32 v164, v134, v160
	ds_bpermute_b32 v165, v134, v161
	ds_bpermute_b32 v166, v134, v162
	ds_bpermute_b32 v167, v134, v163
	s_waitcnt lgkmcnt(0)
	v_add_f32_e32 v160, v160, v164
	v_add_f32_e32 v161, v161, v165
	v_add_f32_e32 v162, v162, v166
	v_add_f32_e32 v163, v163, v167
	ds_bpermute_b32 v164, v135, v160
	ds_bpermute_b32 v165, v135, v161
	ds_bpermute_b32 v166, v135, v162
	ds_bpermute_b32 v167, v135, v163
	s_waitcnt lgkmcnt(0)
	v_add_f32_e32 v160, v160, v164
	v_add_f32_e32 v161, v161, v165
	v_add_f32_e32 v162, v162, v166
	v_add_f32_e32 v163, v163, v167
	v_cndmask_b32_e64 v164, 0, v160, s[12:13]
	v_cndmask_b32_e64 v165, 0, v161, s[12:13]
	v_cndmask_b32_e64 v166, 0, v162, s[12:13]
	v_cndmask_b32_e64 v167, 0, v163, s[12:13]
	s_mov_b64 exec, 0xffff
	global_store_dword v186, v164, s[6:7]
	global_store_dword v187, v165, s[6:7]
	global_store_dword v188, v166, s[6:7]
	global_store_dword v189, v167, s[6:7]
	s_mov_b64 exec, -1
	s_add_i32 s6, s3, 0x3000
	s_lshl_b32 s6, s6, 12
	s_add_u32 s4, s16, s6
	s_addc_u32 s5, s17, 0
	global_load_dwordx4 v[66:69], v140, s[4:5] nt
	global_load_dwordx4 v[70:73], v140, s[4:5] offset:1024 nt
	global_load_dwordx4 v[74:77], v140, s[4:5] offset:2048 nt
	global_load_dwordx4 v[78:81], v140, s[4:5] offset:3072 nt
	global_load_dwordx4 v[82:85], v141, s[4:5] nt
	global_load_dwordx4 v[86:89], v141, s[4:5] offset:1024 nt
	global_load_dwordx4 v[90:93], v141, s[4:5] offset:2048 nt
	global_load_dwordx4 v[94:97], v141, s[4:5] offset:3072 nt
	global_load_dwordx4 v[98:101], v142, s[4:5] nt
	global_load_dwordx4 v[102:105], v142, s[4:5] offset:1024 nt
	global_load_dwordx4 v[106:109], v142, s[4:5] offset:2048 nt
	global_load_dwordx4 v[110:113], v142, s[4:5] offset:3072 nt
	global_load_dwordx4 v[114:117], v143, s[4:5] nt
	global_load_dwordx4 v[118:121], v143, s[4:5] offset:1024 nt
	global_load_dwordx4 v[122:125], v143, s[4:5] offset:2048 nt
	global_load_dwordx4 v[126:129], v143, s[4:5] offset:3072 nt
	s_waitcnt vmcnt(36)
	s_add_i32 s6, s3, 0x2000
	s_lshl_b32 s7, s6, 11
	s_add_u32 s10, s40, s7
	s_addc_u32 s11, s41, 0
	s_lshl_b32 s7, s6, 6
	s_add_u32 s6, s40, s7
	s_addc_u32 s7, s41, 0
	s_add_u32 s6, s6, 0x1f800000
	s_addc_u32 s7, s7, 0
	v_mul_f32_e32 v150, v3, v3
	v_mul_f32_e32 v151, v5, v5
	v_fmac_f32_e32 v150, v2, v2
	v_fmac_f32_e32 v151, v4, v4
	v_add_f32_e32 v160, v150, v151
	v_cvt_pk_f16_f32 v170, v2, v3
	v_cvt_pk_f16_f32 v171, v4, v5
	v_mul_f32_e32 v150, v7, v7
	v_mul_f32_e32 v151, v9, v9
	v_fmac_f32_e32 v150, v6, v6
	v_fmac_f32_e32 v151, v8, v8
	v_add_f32_e32 v152, v150, v151
	v_add_f32_e32 v160, v160, v152
	v_cvt_pk_f16_f32 v172, v6, v7
	v_cvt_pk_f16_f32 v173, v8, v9
	v_mul_f32_e32 v150, v11, v11
	v_mul_f32_e32 v151, v13, v13
	v_fmac_f32_e32 v150, v10, v10
	v_fmac_f32_e32 v151, v12, v12
	v_add_f32_e32 v152, v150, v151
	v_add_f32_e32 v160, v160, v152
	v_cvt_pk_f16_f32 v174, v10, v11
	v_cvt_pk_f16_f32 v175, v12, v13
	v_mul_f32_e32 v150, v15, v15
	v_mul_f32_e32 v151, v17, v17
	v_fmac_f32_e32 v150, v14, v14
	v_fmac_f32_e32 v151, v16, v16
	v_add_f32_e32 v152, v150, v151
	v_add_f32_e32 v160, v160, v152
	v_cvt_pk_f16_f32 v176, v14, v15
	v_cvt_pk_f16_f32 v177, v16, v17
	global_store_dwordx2 v144, v[170:171], s[10:11]
	global_store_dwordx2 v144, v[172:173], s[10:11] offset:512
	global_store_dwordx2 v144, v[174:175], s[10:11] offset:1024
	global_store_dwordx2 v144, v[176:177], s[10:11] offset:1536
	v_mul_f32_e32 v150, v19, v19
	v_mul_f32_e32 v151, v21, v21
	v_fmac_f32_e32 v150, v18, v18
	v_fmac_f32_e32 v151, v20, v20
	v_add_f32_e32 v161, v150, v151
	v_cvt_pk_f16_f32 v178, v18, v19
	v_cvt_pk_f16_f32 v179, v20, v21
	v_mul_f32_e32 v150, v23, v23
	v_mul_f32_e32 v151, v25, v25
	v_fmac_f32_e32 v150, v22, v22
	v_fmac_f32_e32 v151, v24, v24
	v_add_f32_e32 v152, v150, v151
	v_add_f32_e32 v161, v161, v152
	v_cvt_pk_f16_f32 v180, v22, v23
	v_cvt_pk_f16_f32 v181, v24, v25
	v_mul_f32_e32 v150, v27, v27
	v_mul_f32_e32 v151, v29, v29
	v_fmac_f32_e32 v150, v26, v26
	v_fmac_f32_e32 v151, v28, v28
	v_add_f32_e32 v152, v150, v151
	v_add_f32_e32 v161, v161, v152
	v_cvt_pk_f16_f32 v182, v26, v27
	v_cvt_pk_f16_f32 v183, v28, v29
	v_mul_f32_e32 v150, v31, v31
	v_mul_f32_e32 v151, v33, v33
	v_fmac_f32_e32 v150, v30, v30
	v_fmac_f32_e32 v151, v32, v32
	v_add_f32_e32 v152, v150, v151
	v_add_f32_e32 v161, v161, v152
	v_cvt_pk_f16_f32 v184, v30, v31
	v_cvt_pk_f16_f32 v185, v32, v33
	global_store_dwordx2 v145, v[178:179], s[10:11]
	global_store_dwordx2 v145, v[180:181], s[10:11] offset:512
	global_store_dwordx2 v145, v[182:183], s[10:11] offset:1024
	global_store_dwordx2 v145, v[184:185], s[10:11] offset:1536
	v_mul_f32_e32 v150, v35, v35
	v_mul_f32_e32 v151, v37, v37
	v_fmac_f32_e32 v150, v34, v34
	v_fmac_f32_e32 v151, v36, v36
	v_add_f32_e32 v162, v150, v151
	v_cvt_pk_f16_f32 v170, v34, v35
	v_cvt_pk_f16_f32 v171, v36, v37
	v_mul_f32_e32 v150, v39, v39
	v_mul_f32_e32 v151, v41, v41
	v_fmac_f32_e32 v150, v38, v38
	v_fmac_f32_e32 v151, v40, v40
	v_add_f32_e32 v152, v150, v151
; __device__ void p0_xconv(const Args& a) {
;     ...
;         for (int r = 0; r < 4; ++r) {
;             const int row = row0 + r * nwv;
;             if (row < MROWS) {
;                 float ss = 0.f;
; #pragma unroll
;                 for (int i = 0; i < 4; ++i) {
;                     const f32x4 x = v[r][i];
;                     ss += (x[0] * x[0] + x[1] * x[1]) + (x[2] * x[2] + x[3] * x[3]);
;                     f16x4 h; h[0] = (f16)x[0]; h[1] = (f16)x[1]; h[2] = (f16)x[2]; h[3] = (f16)x[3];
;                     *(f16x4*)(XH + (size_t)row * DM + i * 256 + lane * 4) = h;
;                 }
; #pragma unroll
;                 for (int o = 1; o < 64; o <<= 1) ss += __shfl_xor(ss, o);
;                 if (lane < 16) SS[(size_t)row * 16 + lane] = (lane == 0) ? ss : 0.f;
	v_add_f32_e32 v162, v162, v152
	v_cvt_pk_f16_f32 v172, v38, v39
	v_cvt_pk_f16_f32 v173, v40, v41
	v_mul_f32_e32 v150, v43, v43
	v_mul_f32_e32 v151, v45, v45
	v_fmac_f32_e32 v150, v42, v42
	v_fmac_f32_e32 v151, v44, v44
	v_add_f32_e32 v152, v150, v151
	v_add_f32_e32 v162, v162, v152
	v_cvt_pk_f16_f32 v174, v42, v43
	v_cvt_pk_f16_f32 v175, v44, v45
	v_mul_f32_e32 v150, v47, v47
	v_mul_f32_e32 v151, v49, v49
	v_fmac_f32_e32 v150, v46, v46
	v_fmac_f32_e32 v151, v48, v48
	v_add_f32_e32 v152, v150, v151
	v_add_f32_e32 v162, v162, v152
	v_cvt_pk_f16_f32 v176, v46, v47
	v_cvt_pk_f16_f32 v177, v48, v49
	global_store_dwordx2 v146, v[170:171], s[10:11]
	global_store_dwordx2 v146, v[172:173], s[10:11] offset:512
	global_store_dwordx2 v146, v[174:175], s[10:11] offset:1024
	global_store_dwordx2 v146, v[176:177], s[10:11] offset:1536
	v_mul_f32_e32 v150, v51, v51
	v_mul_f32_e32 v151, v53, v53
	v_fmac_f32_e32 v150, v50, v50
	v_fmac_f32_e32 v151, v52, v52
	v_add_f32_e32 v163, v150, v151
	v_cvt_pk_f16_f32 v178, v50, v51
	v_cvt_pk_f16_f32 v179, v52, v53
	v_mul_f32_e32 v150, v55, v55
	v_mul_f32_e32 v151, v57, v57
	v_fmac_f32_e32 v150, v54, v54
	v_fmac_f32_e32 v151, v56, v56
	v_add_f32_e32 v152, v150, v151
	v_add_f32_e32 v163, v163, v152
	v_cvt_pk_f16_f32 v180, v54, v55
	v_cvt_pk_f16_f32 v181, v56, v57
	v_mul_f32_e32 v150, v59, v59
	v_mul_f32_e32 v151, v61, v61
	v_fmac_f32_e32 v150, v58, v58
	v_fmac_f32_e32 v151, v60, v60
	v_add_f32_e32 v152, v150, v151
	v_add_f32_e32 v163, v163, v152
	v_cvt_pk_f16_f32 v182, v58, v59
	v_cvt_pk_f16_f32 v183, v60, v61
	v_mul_f32_e32 v150, v63, v63
	v_mul_f32_e32 v151, v65, v65
	v_fmac_f32_e32 v150, v62, v62
	v_fmac_f32_e32 v151, v64, v64
	v_add_f32_e32 v152, v150, v151
	v_add_f32_e32 v163, v163, v152
	v_cvt_pk_f16_f32 v184, v62, v63
	v_cvt_pk_f16_f32 v185, v64, v65
	global_store_dwordx2 v147, v[178:179], s[10:11]
	global_store_dwordx2 v147, v[180:181], s[10:11] offset:512
	global_store_dwordx2 v147, v[182:183], s[10:11] offset:1024
	global_store_dwordx2 v147, v[184:185], s[10:11] offset:1536
	ds_bpermute_b32 v164, v130, v160
	ds_bpermute_b32 v165, v130, v161
	ds_bpermute_b32 v166, v130, v162
	ds_bpermute_b32 v167, v130, v163
	s_waitcnt lgkmcnt(0)
	v_add_f32_e32 v160, v160, v164
	v_add_f32_e32 v161, v161, v165
	v_add_f32_e32 v162, v162, v166
	v_add_f32_e32 v163, v163, v167
	ds_bpermute_b32 v164, v131, v160
	ds_bpermute_b32 v165, v131, v161
	ds_bpermute_b32 v166, v131, v162
	ds_bpermute_b32 v167, v131, v163
	s_waitcnt lgkmcnt(0)
	v_add_f32_e32 v160, v160, v164
	v_add_f32_e32 v161, v161, v165
	v_add_f32_e32 v162, v162, v166
	v_add_f32_e32 v163, v163, v167
	ds_bpermute_b32 v164, v132, v160
	ds_bpermute_b32 v165, v132, v161
	ds_bpermute_b32 v166, v132, v162
	ds_bpermute_b32 v167, v132, v163
	s_waitcnt lgkmcnt(0)
	v_add_f32_e32 v160, v160, v164
	v_add_f32_e32 v161, v161, v165
	v_add_f32_e32 v162, v162, v166
	v_add_f32_e32 v163, v163, v167
	ds_bpermute_b32 v164, v133, v160
	ds_bpermute_b32 v165, v133, v161
	ds_bpermute_b32 v166, v133, v162
	ds_bpermute_b32 v167, v133, v163
	s_waitcnt lgkmcnt(0)
	v_add_f32_e32 v160, v160, v164
	v_add_f32_e32 v161, v161, v165
	v_add_f32_e32 v162, v162, v166
	v_add_f32_e32 v163, v163, v167
	ds_bpermute_b32 v164, v134, v160
	ds_bpermute_b32 v165, v134, v161
	ds_bpermute_b32 v166, v134, v162
	ds_bpermute_b32 v167, v134, v163
	s_waitcnt lgkmcnt(0)
	v_add_f32_e32 v160, v160, v164
	v_add_f32_e32 v161, v161, v165
	v_add_f32_e32 v162, v162, v166
	v_add_f32_e32 v163, v163, v167
	ds_bpermute_b32 v164, v135, v160
	ds_bpermute_b32 v165, v135, v161
	ds_bpermute_b32 v166, v135, v162
	ds_bpermute_b32 v167, v135, v163
	s_waitcnt lgkmcnt(0)
	v_add_f32_e32 v160, v160, v164
	v_add_f32_e32 v161, v161, v165
	v_add_f32_e32 v162, v162, v166
	v_add_f32_e32 v163, v163, v167
	v_cndmask_b32_e64 v164, 0, v160, s[12:13]
	v_cndmask_b32_e64 v165, 0, v161, s[12:13]
	v_cndmask_b32_e64 v166, 0, v162, s[12:13]
	v_cndmask_b32_e64 v167, 0, v163, s[12:13]
	s_mov_b64 exec, 0xffff
	global_store_dword v186, v164, s[6:7]
	global_store_dword v187, v165, s[6:7]
	global_store_dword v188, v166, s[6:7]
	global_store_dword v189, v167, s[6:7]
	s_mov_b64 exec, -1
	s_add_i32 s6, s3, 0x0
	s_lshl_b32 s6, s6, 12
	s_add_u32 s4, s18, s6
	s_addc_u32 s5, s19, 0
	global_load_dwordx4 v[2:5], v140, s[4:5] nt
	global_load_dwordx4 v[6:9], v140, s[4:5] offset:1024 nt
	global_load_dwordx4 v[10:13], v140, s[4:5] offset:2048 nt
	global_load_dwordx4 v[14:17], v140, s[4:5] offset:3072 nt
	global_load_dwordx4 v[18:21], v141, s[4:5] nt
	global_load_dwordx4 v[22:25], v141, s[4:5] offset:1024 nt
	global_load_dwordx4 v[26:29], v141, s[4:5] offset:2048 nt
	global_load_dwordx4 v[30:33], v141, s[4:5] offset:3072 nt
	global_load_dwordx4 v[34:37], v142, s[4:5] nt
	global_load_dwordx4 v[38:41], v142, s[4:5] offset:1024 nt
	global_load_dwordx4 v[42:45], v142, s[4:5] offset:2048 nt
	global_load_dwordx4 v[46:49], v142, s[4:5] offset:3072 nt
	global_load_dwordx4 v[50:53], v143, s[4:5] nt
	global_load_dwordx4 v[54:57], v143, s[4:5] offset:1024 nt
	global_load_dwordx4 v[58:61], v143, s[4:5] offset:2048 nt
	global_load_dwordx4 v[62:65], v143, s[4:5] offset:3072 nt
	s_waitcnt vmcnt(36)
; __device__ void p0_xconv(const Args& a) {
;     ...
;             if (row < MROWS) {
;                 const float* src = (row < ROWS_PROMPT) ? a.x_prompt + (size_t)row * DM : a.x_sample + (size_t)(row - ROWS_PROMPT) * DM;
; #pragma unroll
;                 for (int i = 0; i < 4; ++i) v[r][i] = __builtin_nontemporal_load((const f32x4*)(src + i * 256 + lane * 4));
;             }
;         }
; #pragma unroll
;         for (int r = 0; r < 4; ++r) {
;             const int row = row0 + r * nwv;
;             if (row < MROWS) {
;                 float ss = 0.f;
; #pragma unroll
;                 for (int i = 0; i < 4; ++i) {
;                     const f32x4 x = v[r][i];
;                     ss += (x[0] * x[0] + x[1] * x[1]) + (x[2] * x[2] + x[3] * x[3]);
;                     f16x4 h; h[0] = (f16)x[0]; h[1] = (f16)x[1]; h[2] = (f16)x[2]; h[3] = (f16)x[3];
;                     *(f16x4*)(XH + (size_t)row * DM + i * 256 + lane * 4) = h;
;                 }
; #pragma unroll
;                 for (int o = 1; o < 64; o <<= 1) ss += __shfl_xor(ss, o);
	s_add_i32 s6, s3, 0x3000
	s_lshl_b32 s7, s6, 11
	s_add_u32 s10, s40, s7
	s_addc_u32 s11, s41, 0
	s_lshl_b32 s7, s6, 6
	s_add_u32 s6, s40, s7
	s_addc_u32 s7, s41, 0
	s_add_u32 s6, s6, 0x1f800000
	s_addc_u32 s7, s7, 0
	v_mul_f32_e32 v150, v67, v67
	v_mul_f32_e32 v151, v69, v69
	v_fmac_f32_e32 v150, v66, v66
	v_fmac_f32_e32 v151, v68, v68
	v_add_f32_e32 v160, v150, v151
	v_cvt_pk_f16_f32 v170, v66, v67
	v_cvt_pk_f16_f32 v171, v68, v69
	v_mul_f32_e32 v150, v71, v71
	v_mul_f32_e32 v151, v73, v73
	v_fmac_f32_e32 v150, v70, v70
	v_fmac_f32_e32 v151, v72, v72
	v_add_f32_e32 v152, v150, v151
	v_add_f32_e32 v160, v160, v152
	v_cvt_pk_f16_f32 v172, v70, v71
	v_cvt_pk_f16_f32 v173, v72, v73
	v_mul_f32_e32 v150, v75, v75
	v_mul_f32_e32 v151, v77, v77
	v_fmac_f32_e32 v150, v74, v74
	v_fmac_f32_e32 v151, v76, v76
	v_add_f32_e32 v152, v150, v151
	v_add_f32_e32 v160, v160, v152
	v_cvt_pk_f16_f32 v174, v74, v75
	v_cvt_pk_f16_f32 v175, v76, v77
	v_mul_f32_e32 v150, v79, v79
	v_mul_f32_e32 v151, v81, v81
	v_fmac_f32_e32 v150, v78, v78
	v_fmac_f32_e32 v151, v80, v80
	v_add_f32_e32 v152, v150, v151
	v_add_f32_e32 v160, v160, v152
	v_cvt_pk_f16_f32 v176, v78, v79
	v_cvt_pk_f16_f32 v177, v80, v81
	global_store_dwordx2 v144, v[170:171], s[10:11]
	global_store_dwordx2 v144, v[172:173], s[10:11] offset:512
	global_store_dwordx2 v144, v[174:175], s[10:11] offset:1024
	global_store_dwordx2 v144, v[176:177], s[10:11] offset:1536
	v_mul_f32_e32 v150, v83, v83
	v_mul_f32_e32 v151, v85, v85
	v_fmac_f32_e32 v150, v82, v82
	v_fmac_f32_e32 v151, v84, v84
	v_add_f32_e32 v161, v150, v151
	v_cvt_pk_f16_f32 v178, v82, v83
	v_cvt_pk_f16_f32 v179, v84, v85
	v_mul_f32_e32 v150, v87, v87
	v_mul_f32_e32 v151, v89, v89
	v_fmac_f32_e32 v150, v86, v86
	v_fmac_f32_e32 v151, v88, v88
	v_add_f32_e32 v152, v150, v151
	v_add_f32_e32 v161, v161, v152
	v_cvt_pk_f16_f32 v180, v86, v87
	v_cvt_pk_f16_f32 v181, v88, v89
	v_mul_f32_e32 v150, v91, v91
	v_mul_f32_e32 v151, v93, v93
	v_fmac_f32_e32 v150, v90, v90
	v_fmac_f32_e32 v151, v92, v92
	v_add_f32_e32 v152, v150, v151
	v_add_f32_e32 v161, v161, v152
	v_cvt_pk_f16_f32 v182, v90, v91
	v_cvt_pk_f16_f32 v183, v92, v93
	v_mul_f32_e32 v150, v95, v95
	v_mul_f32_e32 v151, v97, v97
	v_fmac_f32_e32 v150, v94, v94
	v_fmac_f32_e32 v151, v96, v96
	v_add_f32_e32 v152, v150, v151
	v_add_f32_e32 v161, v161, v152
	v_cvt_pk_f16_f32 v184, v94, v95
	v_cvt_pk_f16_f32 v185, v96, v97
	global_store_dwordx2 v145, v[178:179], s[10:11]
	global_store_dwordx2 v145, v[180:181], s[10:11] offset:512
	global_store_dwordx2 v145, v[182:183], s[10:11] offset:1024
	global_store_dwordx2 v145, v[184:185], s[10:11] offset:1536
	v_mul_f32_e32 v150, v99, v99
	v_mul_f32_e32 v151, v101, v101
	v_fmac_f32_e32 v150, v98, v98
	v_fmac_f32_e32 v151, v100, v100
	v_add_f32_e32 v162, v150, v151
	v_cvt_pk_f16_f32 v170, v98, v99
	v_cvt_pk_f16_f32 v171, v100, v101
	v_mul_f32_e32 v150, v103, v103
	v_mul_f32_e32 v151, v105, v105
	v_fmac_f32_e32 v150, v102, v102
	v_fmac_f32_e32 v151, v104, v104
	v_add_f32_e32 v152, v150, v151
	v_add_f32_e32 v162, v162, v152
	v_cvt_pk_f16_f32 v172, v102, v103
	v_cvt_pk_f16_f32 v173, v104, v105
	v_mul_f32_e32 v150, v107, v107
	v_mul_f32_e32 v151, v109, v109
	v_fmac_f32_e32 v150, v106, v106
	v_fmac_f32_e32 v151, v108, v108
	v_add_f32_e32 v152, v150, v151
	v_add_f32_e32 v162, v162, v152
	v_cvt_pk_f16_f32 v174, v106, v107
	v_cvt_pk_f16_f32 v175, v108, v109
	v_mul_f32_e32 v150, v111, v111
	v_mul_f32_e32 v151, v113, v113
	v_fmac_f32_e32 v150, v110, v110
	v_fmac_f32_e32 v151, v112, v112
	v_add_f32_e32 v152, v150, v151
	v_add_f32_e32 v162, v162, v152
	v_cvt_pk_f16_f32 v176, v110, v111
	v_cvt_pk_f16_f32 v177, v112, v113
	global_store_dwordx2 v146, v[170:171], s[10:11]
	global_store_dwordx2 v146, v[172:173], s[10:11] offset:512
	global_store_dwordx2 v146, v[174:175], s[10:11] offset:1024
	global_store_dwordx2 v146, v[176:177], s[10:11] offset:1536
	v_mul_f32_e32 v150, v115, v115
	v_mul_f32_e32 v151, v117, v117
	v_fmac_f32_e32 v150, v114, v114
	v_fmac_f32_e32 v151, v116, v116
	v_add_f32_e32 v163, v150, v151
	v_cvt_pk_f16_f32 v178, v114, v115
	v_cvt_pk_f16_f32 v179, v116, v117
	v_mul_f32_e32 v150, v119, v119
	v_mul_f32_e32 v151, v121, v121
	v_fmac_f32_e32 v150, v118, v118
	v_fmac_f32_e32 v151, v120, v120
	v_add_f32_e32 v152, v150, v151
	v_add_f32_e32 v163, v163, v152
	v_cvt_pk_f16_f32 v180, v118, v119
	v_cvt_pk_f16_f32 v181, v120, v121
	v_mul_f32_e32 v150, v123, v123
	v_mul_f32_e32 v151, v125, v125
	v_fmac_f32_e32 v150, v122, v122
	v_fmac_f32_e32 v151, v124, v124
	v_add_f32_e32 v152, v150, v151
	v_add_f32_e32 v163, v163, v152
	v_cvt_pk_f16_f32 v182, v122, v123
	v_cvt_pk_f16_f32 v183, v124, v125
	v_mul_f32_e32 v150, v127, v127
	v_mul_f32_e32 v151, v129, v129
	v_fmac_f32_e32 v150, v126, v126
	v_fmac_f32_e32 v151, v128, v128
	v_add_f32_e32 v152, v150, v151
	v_add_f32_e32 v163, v163, v152
	v_cvt_pk_f16_f32 v184, v126, v127
	v_cvt_pk_f16_f32 v185, v128, v129
	global_store_dwordx2 v147, v[178:179], s[10:11]
	global_store_dwordx2 v147, v[180:181], s[10:11] offset:512
	global_store_dwordx2 v147, v[182:183], s[10:11] offset:1024
	global_store_dwordx2 v147, v[184:185], s[10:11] offset:1536
	ds_bpermute_b32 v164, v130, v160
	ds_bpermute_b32 v165, v130, v161
	ds_bpermute_b32 v166, v130, v162
	ds_bpermute_b32 v167, v130, v163
	s_waitcnt lgkmcnt(0)
	v_add_f32_e32 v160, v160, v164
	v_add_f32_e32 v161, v161, v165
	v_add_f32_e32 v162, v162, v166
	v_add_f32_e32 v163, v163, v167
	ds_bpermute_b32 v164, v131, v160
	ds_bpermute_b32 v165, v131, v161
	ds_bpermute_b32 v166, v131, v162
	ds_bpermute_b32 v167, v131, v163
	s_waitcnt lgkmcnt(0)
; __device__ void p0_xconv(const Args& a) {
;     ...
;     for (int row0 = (int)blockIdx.x * 8 + wv; row0 < MROWS; row0 += 4 * nwv) {
;         f32x4 v[4][4];
; #pragma unroll
;         for (int r = 0; r < 4; ++r) {
;             const int row = row0 + r * nwv;
;             if (row < MROWS) {
;                 const float* src = (row < ROWS_PROMPT) ? a.x_prompt + (size_t)row * DM : a.x_sample + (size_t)(row - ROWS_PROMPT) * DM;
; #pragma unroll
;                 for (int i = 0; i < 4; ++i) v[r][i] = __builtin_nontemporal_load((const f32x4*)(src + i * 256 + lane * 4));
;             }
;         }
; #pragma unroll
;         for (int r = 0; r < 4; ++r) {
;             const int row = row0 + r * nwv;
;             if (row < MROWS) {
;                 float ss = 0.f;
; #pragma unroll
;                 for (int i = 0; i < 4; ++i) {
;                     const f32x4 x = v[r][i];
;                     ss += (x[0] * x[0] + x[1] * x[1]) + (x[2] * x[2] + x[3] * x[3]);
;                     f16x4 h; h[0] = (f16)x[0]; h[1] = (f16)x[1]; h[2] = (f16)x[2]; h[3] = (f16)x[3];
;                     *(f16x4*)(XH + (size_t)row * DM + i * 256 + lane * 4) = h;
;                 }
; #pragma unroll
;                 for (int o = 1; o < 64; o <<= 1) ss += __shfl_xor(ss, o);
;                 if (lane < 16) SS[(size_t)row * 16 + lane] = (lane == 0) ? ss : 0.f;
	v_add_f32_e32 v160, v160, v164
	v_add_f32_e32 v161, v161, v165
	v_add_f32_e32 v162, v162, v166
	v_add_f32_e32 v163, v163, v167
	ds_bpermute_b32 v164, v132, v160
	ds_bpermute_b32 v165, v132, v161
	ds_bpermute_b32 v166, v132, v162
	ds_bpermute_b32 v167, v132, v163
	s_waitcnt lgkmcnt(0)
	v_add_f32_e32 v160, v160, v164
	v_add_f32_e32 v161, v161, v165
	v_add_f32_e32 v162, v162, v166
	v_add_f32_e32 v163, v163, v167
	ds_bpermute_b32 v164, v133, v160
	ds_bpermute_b32 v165, v133, v161
	ds_bpermute_b32 v166, v133, v162
	ds_bpermute_b32 v167, v133, v163
	s_waitcnt lgkmcnt(0)
	v_add_f32_e32 v160, v160, v164
	v_add_f32_e32 v161, v161, v165
	v_add_f32_e32 v162, v162, v166
	v_add_f32_e32 v163, v163, v167
	ds_bpermute_b32 v164, v134, v160
	ds_bpermute_b32 v165, v134, v161
	ds_bpermute_b32 v166, v134, v162
	ds_bpermute_b32 v167, v134, v163
	s_waitcnt lgkmcnt(0)
	v_add_f32_e32 v160, v160, v164
	v_add_f32_e32 v161, v161, v165
	v_add_f32_e32 v162, v162, v166
	v_add_f32_e32 v163, v163, v167
	ds_bpermute_b32 v164, v135, v160
	ds_bpermute_b32 v165, v135, v161
	ds_bpermute_b32 v166, v135, v162
	ds_bpermute_b32 v167, v135, v163
	s_waitcnt lgkmcnt(0)
	v_add_f32_e32 v160, v160, v164
	v_add_f32_e32 v161, v161, v165
	v_add_f32_e32 v162, v162, v166
	v_add_f32_e32 v163, v163, v167
	v_cndmask_b32_e64 v164, 0, v160, s[12:13]
	v_cndmask_b32_e64 v165, 0, v161, s[12:13]
	v_cndmask_b32_e64 v166, 0, v162, s[12:13]
	v_cndmask_b32_e64 v167, 0, v163, s[12:13]
	s_mov_b64 exec, 0xffff
	global_store_dword v186, v164, s[6:7]
	global_store_dword v187, v165, s[6:7]
	global_store_dword v188, v166, s[6:7]
	global_store_dword v189, v167, s[6:7]
	s_mov_b64 exec, -1
	s_add_i32 s6, s3, 0x1000
	s_lshl_b32 s6, s6, 12
	s_add_u32 s4, s18, s6
	s_addc_u32 s5, s19, 0
	global_load_dwordx4 v[66:69], v140, s[4:5] nt
	global_load_dwordx4 v[70:73], v140, s[4:5] offset:1024 nt
	global_load_dwordx4 v[74:77], v140, s[4:5] offset:2048 nt
	global_load_dwordx4 v[78:81], v140, s[4:5] offset:3072 nt
	global_load_dwordx4 v[82:85], v141, s[4:5] nt
	global_load_dwordx4 v[86:89], v141, s[4:5] offset:1024 nt
	global_load_dwordx4 v[90:93], v141, s[4:5] offset:2048 nt
	global_load_dwordx4 v[94:97], v141, s[4:5] offset:3072 nt
	global_load_dwordx4 v[98:101], v142, s[4:5] nt
	global_load_dwordx4 v[102:105], v142, s[4:5] offset:1024 nt
	global_load_dwordx4 v[106:109], v142, s[4:5] offset:2048 nt
	global_load_dwordx4 v[110:113], v142, s[4:5] offset:3072 nt
	global_load_dwordx4 v[114:117], v143, s[4:5] nt
	global_load_dwordx4 v[118:121], v143, s[4:5] offset:1024 nt
	global_load_dwordx4 v[122:125], v143, s[4:5] offset:2048 nt
	global_load_dwordx4 v[126:129], v143, s[4:5] offset:3072 nt
	s_waitcnt vmcnt(36)
	s_add_i32 s6, s3, 0x4000
	s_lshl_b32 s7, s6, 11
	s_add_u32 s10, s40, s7
	s_addc_u32 s11, s41, 0
	s_lshl_b32 s7, s6, 6
	s_add_u32 s6, s40, s7
	s_addc_u32 s7, s41, 0
	s_add_u32 s6, s6, 0x1f800000
	s_addc_u32 s7, s7, 0
	v_mul_f32_e32 v150, v3, v3
	v_mul_f32_e32 v151, v5, v5
	v_fmac_f32_e32 v150, v2, v2
	v_fmac_f32_e32 v151, v4, v4
	v_add_f32_e32 v160, v150, v151
	v_cvt_pk_f16_f32 v170, v2, v3
	v_cvt_pk_f16_f32 v171, v4, v5
	v_mul_f32_e32 v150, v7, v7
	v_mul_f32_e32 v151, v9, v9
	v_fmac_f32_e32 v150, v6, v6
	v_fmac_f32_e32 v151, v8, v8
	v_add_f32_e32 v152, v150, v151
	v_add_f32_e32 v160, v160, v152
	v_cvt_pk_f16_f32 v172, v6, v7
	v_cvt_pk_f16_f32 v173, v8, v9
	v_mul_f32_e32 v150, v11, v11
	v_mul_f32_e32 v151, v13, v13
	v_fmac_f32_e32 v150, v10, v10
	v_fmac_f32_e32 v151, v12, v12
	v_add_f32_e32 v152, v150, v151
	v_add_f32_e32 v160, v160, v152
	v_cvt_pk_f16_f32 v174, v10, v11
	v_cvt_pk_f16_f32 v175, v12, v13
	v_mul_f32_e32 v150, v15, v15
	v_mul_f32_e32 v151, v17, v17
	v_fmac_f32_e32 v150, v14, v14
	v_fmac_f32_e32 v151, v16, v16
	v_add_f32_e32 v152, v150, v151
	v_add_f32_e32 v160, v160, v152
	v_cvt_pk_f16_f32 v176, v14, v15
	v_cvt_pk_f16_f32 v177, v16, v17
	global_store_dwordx2 v144, v[170:171], s[10:11]
	global_store_dwordx2 v144, v[172:173], s[10:11] offset:512
	global_store_dwordx2 v144, v[174:175], s[10:11] offset:1024
	global_store_dwordx2 v144, v[176:177], s[10:11] offset:1536
	v_mul_f32_e32 v150, v19, v19
	v_mul_f32_e32 v151, v21, v21
	v_fmac_f32_e32 v150, v18, v18
	v_fmac_f32_e32 v151, v20, v20
	v_add_f32_e32 v161, v150, v151
	v_cvt_pk_f16_f32 v178, v18, v19
	v_cvt_pk_f16_f32 v179, v20, v21
	v_mul_f32_e32 v150, v23, v23
	v_mul_f32_e32 v151, v25, v25
	v_fmac_f32_e32 v150, v22, v22
	v_fmac_f32_e32 v151, v24, v24
	v_add_f32_e32 v152, v150, v151
	v_add_f32_e32 v161, v161, v152
	v_cvt_pk_f16_f32 v180, v22, v23
	v_cvt_pk_f16_f32 v181, v24, v25
	v_mul_f32_e32 v150, v27, v27
	v_mul_f32_e32 v151, v29, v29
	v_fmac_f32_e32 v150, v26, v26
	v_fmac_f32_e32 v151, v28, v28
	v_add_f32_e32 v152, v150, v151
	v_add_f32_e32 v161, v161, v152
	v_cvt_pk_f16_f32 v182, v26, v27
	v_cvt_pk_f16_f32 v183, v28, v29
	v_mul_f32_e32 v150, v31, v31
	v_mul_f32_e32 v151, v33, v33
	v_fmac_f32_e32 v150, v30, v30
	v_fmac_f32_e32 v151, v32, v32
	v_add_f32_e32 v152, v150, v151
	v_add_f32_e32 v161, v161, v152
	v_cvt_pk_f16_f32 v184, v30, v31
	v_cvt_pk_f16_f32 v185, v32, v33
	global_store_dwordx2 v145, v[178:179], s[10:11]
	global_store_dwordx2 v145, v[180:181], s[10:11] offset:512
	global_store_dwordx2 v145, v[182:183], s[10:11] offset:1024
	global_store_dwordx2 v145, v[184:185], s[10:11] offset:1536
	v_mul_f32_e32 v150, v35, v35
	v_mul_f32_e32 v151, v37, v37
	v_fmac_f32_e32 v150, v34, v34
	v_fmac_f32_e32 v151, v36, v36
	v_add_f32_e32 v162, v150, v151
	v_cvt_pk_f16_f32 v170, v34, v35
	v_cvt_pk_f16_f32 v171, v36, v37
	v_mul_f32_e32 v150, v39, v39
	v_mul_f32_e32 v151, v41, v41
	v_fmac_f32_e32 v150, v38, v38
	v_fmac_f32_e32 v151, v40, v40
	v_add_f32_e32 v152, v150, v151
; __device__ void p0_xconv(const Args& a) {
;     ...
;     for (int row0 = (int)blockIdx.x * 8 + wv; row0 < MROWS; row0 += 4 * nwv) {
;         f32x4 v[4][4];
; #pragma unroll
;         for (int r = 0; r < 4; ++r) {
;             const int row = row0 + r * nwv;
;             if (row < MROWS) {
;                 const float* src = (row < ROWS_PROMPT) ? a.x_prompt + (size_t)row * DM : a.x_sample + (size_t)(row - ROWS_PROMPT) * DM;
; #pragma unroll
;                 for (int i = 0; i < 4; ++i) v[r][i] = __builtin_nontemporal_load((const f32x4*)(src + i * 256 + lane * 4));
;             }
;         }
; #pragma unroll
;         for (int r = 0; r < 4; ++r) {
;             const int row = row0 + r * nwv;
;             if (row < MROWS) {
;                 float ss = 0.f;
; #pragma unroll
;                 for (int i = 0; i < 4; ++i) {
;                     const f32x4 x = v[r][i];
;                     ss += (x[0] * x[0] + x[1] * x[1]) + (x[2] * x[2] + x[3] * x[3]);
;                     f16x4 h; h[0] = (f16)x[0]; h[1] = (f16)x[1]; h[2] = (f16)x[2]; h[3] = (f16)x[3];
;                     *(f16x4*)(XH + (size_t)row * DM + i * 256 + lane * 4) = h;
;                 }
; #pragma unroll
;                 for (int o = 1; o < 64; o <<= 1) ss += __shfl_xor(ss, o);
;                 if (lane < 16) SS[(size_t)row * 16 + lane] = (lane == 0) ? ss : 0.f;
	v_add_f32_e32 v162, v162, v152
	v_cvt_pk_f16_f32 v172, v38, v39
	v_cvt_pk_f16_f32 v173, v40, v41
	v_mul_f32_e32 v150, v43, v43
	v_mul_f32_e32 v151, v45, v45
	v_fmac_f32_e32 v150, v42, v42
	v_fmac_f32_e32 v151, v44, v44
	v_add_f32_e32 v152, v150, v151
	v_add_f32_e32 v162, v162, v152
	v_cvt_pk_f16_f32 v174, v42, v43
	v_cvt_pk_f16_f32 v175, v44, v45
	v_mul_f32_e32 v150, v47, v47
	v_mul_f32_e32 v151, v49, v49
	v_fmac_f32_e32 v150, v46, v46
	v_fmac_f32_e32 v151, v48, v48
	v_add_f32_e32 v152, v150, v151
	v_add_f32_e32 v162, v162, v152
	v_cvt_pk_f16_f32 v176, v46, v47
	v_cvt_pk_f16_f32 v177, v48, v49
	global_store_dwordx2 v146, v[170:171], s[10:11]
	global_store_dwordx2 v146, v[172:173], s[10:11] offset:512
	global_store_dwordx2 v146, v[174:175], s[10:11] offset:1024
	global_store_dwordx2 v146, v[176:177], s[10:11] offset:1536
	v_mul_f32_e32 v150, v51, v51
	v_mul_f32_e32 v151, v53, v53
	v_fmac_f32_e32 v150, v50, v50
	v_fmac_f32_e32 v151, v52, v52
	v_add_f32_e32 v163, v150, v151
	v_cvt_pk_f16_f32 v178, v50, v51
	v_cvt_pk_f16_f32 v179, v52, v53
	v_mul_f32_e32 v150, v55, v55
	v_mul_f32_e32 v151, v57, v57
	v_fmac_f32_e32 v150, v54, v54
	v_fmac_f32_e32 v151, v56, v56
	v_add_f32_e32 v152, v150, v151
	v_add_f32_e32 v163, v163, v152
	v_cvt_pk_f16_f32 v180, v54, v55
	v_cvt_pk_f16_f32 v181, v56, v57
	v_mul_f32_e32 v150, v59, v59
	v_mul_f32_e32 v151, v61, v61
	v_fmac_f32_e32 v150, v58, v58
	v_fmac_f32_e32 v151, v60, v60
	v_add_f32_e32 v152, v150, v151
	v_add_f32_e32 v163, v163, v152
	v_cvt_pk_f16_f32 v182, v58, v59
	v_cvt_pk_f16_f32 v183, v60, v61
	v_mul_f32_e32 v150, v63, v63
	v_mul_f32_e32 v151, v65, v65
	v_fmac_f32_e32 v150, v62, v62
	v_fmac_f32_e32 v151, v64, v64
	v_add_f32_e32 v152, v150, v151
	v_add_f32_e32 v163, v163, v152
	v_cvt_pk_f16_f32 v184, v62, v63
	v_cvt_pk_f16_f32 v185, v64, v65
	global_store_dwordx2 v147, v[178:179], s[10:11]
	global_store_dwordx2 v147, v[180:181], s[10:11] offset:512
	global_store_dwordx2 v147, v[182:183], s[10:11] offset:1024
	global_store_dwordx2 v147, v[184:185], s[10:11] offset:1536
	ds_bpermute_b32 v164, v130, v160
	ds_bpermute_b32 v165, v130, v161
	ds_bpermute_b32 v166, v130, v162
	ds_bpermute_b32 v167, v130, v163
	s_waitcnt lgkmcnt(0)
	v_add_f32_e32 v160, v160, v164
	v_add_f32_e32 v161, v161, v165
	v_add_f32_e32 v162, v162, v166
	v_add_f32_e32 v163, v163, v167
	ds_bpermute_b32 v164, v131, v160
	ds_bpermute_b32 v165, v131, v161
	ds_bpermute_b32 v166, v131, v162
	ds_bpermute_b32 v167, v131, v163
	s_waitcnt lgkmcnt(0)
	v_add_f32_e32 v160, v160, v164
	v_add_f32_e32 v161, v161, v165
	v_add_f32_e32 v162, v162, v166
	v_add_f32_e32 v163, v163, v167
	ds_bpermute_b32 v164, v132, v160
	ds_bpermute_b32 v165, v132, v161
	ds_bpermute_b32 v166, v132, v162
	ds_bpermute_b32 v167, v132, v163
	s_waitcnt lgkmcnt(0)
	v_add_f32_e32 v160, v160, v164
	v_add_f32_e32 v161, v161, v165
	v_add_f32_e32 v162, v162, v166
	v_add_f32_e32 v163, v163, v167
	ds_bpermute_b32 v164, v133, v160
	ds_bpermute_b32 v165, v133, v161
	ds_bpermute_b32 v166, v133, v162
	ds_bpermute_b32 v167, v133, v163
	s_waitcnt lgkmcnt(0)
	v_add_f32_e32 v160, v160, v164
	v_add_f32_e32 v161, v161, v165
	v_add_f32_e32 v162, v162, v166
	v_add_f32_e32 v163, v163, v167
	ds_bpermute_b32 v164, v134, v160
	ds_bpermute_b32 v165, v134, v161
	ds_bpermute_b32 v166, v134, v162
	ds_bpermute_b32 v167, v134, v163
	s_waitcnt lgkmcnt(0)
	v_add_f32_e32 v160, v160, v164
	v_add_f32_e32 v161, v161, v165
	v_add_f32_e32 v162, v162, v166
	v_add_f32_e32 v163, v163, v167
	ds_bpermute_b32 v164, v135, v160
	ds_bpermute_b32 v165, v135, v161
	ds_bpermute_b32 v166, v135, v162
	ds_bpermute_b32 v167, v135, v163
	s_waitcnt lgkmcnt(0)
	v_add_f32_e32 v160, v160, v164
	v_add_f32_e32 v161, v161, v165
	v_add_f32_e32 v162, v162, v166
	v_add_f32_e32 v163, v163, v167
	v_cndmask_b32_e64 v164, 0, v160, s[12:13]
	v_cndmask_b32_e64 v165, 0, v161, s[12:13]
	v_cndmask_b32_e64 v166, 0, v162, s[12:13]
	v_cndmask_b32_e64 v167, 0, v163, s[12:13]
	s_mov_b64 exec, 0xffff
	global_store_dword v186, v164, s[6:7]
	global_store_dword v187, v165, s[6:7]
	global_store_dword v188, v166, s[6:7]
	global_store_dword v189, v167, s[6:7]
	s_mov_b64 exec, -1
	s_add_i32 s6, s3, 0x2000
	s_lshl_b32 s6, s6, 12
	s_add_u32 s4, s18, s6
	s_addc_u32 s5, s19, 0
	global_load_dwordx4 v[2:5], v140, s[4:5] nt
	global_load_dwordx4 v[6:9], v140, s[4:5] offset:1024 nt
	global_load_dwordx4 v[10:13], v140, s[4:5] offset:2048 nt
	global_load_dwordx4 v[14:17], v140, s[4:5] offset:3072 nt
	global_load_dwordx4 v[18:21], v141, s[4:5] nt
	global_load_dwordx4 v[22:25], v141, s[4:5] offset:1024 nt
	global_load_dwordx4 v[26:29], v141, s[4:5] offset:2048 nt
	global_load_dwordx4 v[30:33], v141, s[4:5] offset:3072 nt
	global_load_dwordx4 v[34:37], v142, s[4:5] nt
	global_load_dwordx4 v[38:41], v142, s[4:5] offset:1024 nt
	global_load_dwordx4 v[42:45], v142, s[4:5] offset:2048 nt
	global_load_dwordx4 v[46:49], v142, s[4:5] offset:3072 nt
	global_load_dwordx4 v[50:53], v143, s[4:5] nt
	global_load_dwordx4 v[54:57], v143, s[4:5] offset:1024 nt
	global_load_dwordx4 v[58:61], v143, s[4:5] offset:2048 nt
	global_load_dwordx4 v[62:65], v143, s[4:5] offset:3072 nt
	s_waitcnt vmcnt(36)
; __device__ void p0_xconv(const Args& a) {
;     ...
;             if (row < MROWS) {
;                 const float* src = (row < ROWS_PROMPT) ? a.x_prompt + (size_t)row * DM : a.x_sample + (size_t)(row - ROWS_PROMPT) * DM;
; #pragma unroll
;                 for (int i = 0; i < 4; ++i) v[r][i] = __builtin_nontemporal_load((const f32x4*)(src + i * 256 + lane * 4));
;             }
;         }
; #pragma unroll
;         for (int r = 0; r < 4; ++r) {
;             const int row = row0 + r * nwv;
;             if (row < MROWS) {
;                 float ss = 0.f;
; #pragma unroll
;                 for (int i = 0; i < 4; ++i) {
;                     const f32x4 x = v[r][i];
;                     ss += (x[0] * x[0] + x[1] * x[1]) + (x[2] * x[2] + x[3] * x[3]);
;                     f16x4 h; h[0] = (f16)x[0]; h[1] = (f16)x[1]; h[2] = (f16)x[2]; h[3] = (f16)x[3];
;                     *(f16x4*)(XH + (size_t)row * DM + i * 256 + lane * 4) = h;
;                 }
; #pragma unroll
;                 for (int o = 1; o < 64; o <<= 1) ss += __shfl_xor(ss, o);
	s_add_i32 s6, s3, 0x5000
	s_lshl_b32 s7, s6, 11
	s_add_u32 s10, s40, s7
	s_addc_u32 s11, s41, 0
	s_lshl_b32 s7, s6, 6
	s_add_u32 s6, s40, s7
	s_addc_u32 s7, s41, 0
	s_add_u32 s6, s6, 0x1f800000
	s_addc_u32 s7, s7, 0
	v_mul_f32_e32 v150, v67, v67
	v_mul_f32_e32 v151, v69, v69
	v_fmac_f32_e32 v150, v66, v66
	v_fmac_f32_e32 v151, v68, v68
	v_add_f32_e32 v160, v150, v151
	v_cvt_pk_f16_f32 v170, v66, v67
	v_cvt_pk_f16_f32 v171, v68, v69
	v_mul_f32_e32 v150, v71, v71
	v_mul_f32_e32 v151, v73, v73
	v_fmac_f32_e32 v150, v70, v70
	v_fmac_f32_e32 v151, v72, v72
	v_add_f32_e32 v152, v150, v151
	v_add_f32_e32 v160, v160, v152
	v_cvt_pk_f16_f32 v172, v70, v71
	v_cvt_pk_f16_f32 v173, v72, v73
	v_mul_f32_e32 v150, v75, v75
	v_mul_f32_e32 v151, v77, v77
	v_fmac_f32_e32 v150, v74, v74
	v_fmac_f32_e32 v151, v76, v76
	v_add_f32_e32 v152, v150, v151
	v_add_f32_e32 v160, v160, v152
	v_cvt_pk_f16_f32 v174, v74, v75
	v_cvt_pk_f16_f32 v175, v76, v77
	v_mul_f32_e32 v150, v79, v79
	v_mul_f32_e32 v151, v81, v81
	v_fmac_f32_e32 v150, v78, v78
	v_fmac_f32_e32 v151, v80, v80
	v_add_f32_e32 v152, v150, v151
	v_add_f32_e32 v160, v160, v152
	v_cvt_pk_f16_f32 v176, v78, v79
	v_cvt_pk_f16_f32 v177, v80, v81
	global_store_dwordx2 v144, v[170:171], s[10:11]
	global_store_dwordx2 v144, v[172:173], s[10:11] offset:512
	global_store_dwordx2 v144, v[174:175], s[10:11] offset:1024
	global_store_dwordx2 v144, v[176:177], s[10:11] offset:1536
	v_mul_f32_e32 v150, v83, v83
	v_mul_f32_e32 v151, v85, v85
	v_fmac_f32_e32 v150, v82, v82
	v_fmac_f32_e32 v151, v84, v84
	v_add_f32_e32 v161, v150, v151
	v_cvt_pk_f16_f32 v178, v82, v83
	v_cvt_pk_f16_f32 v179, v84, v85
	v_mul_f32_e32 v150, v87, v87
	v_mul_f32_e32 v151, v89, v89
	v_fmac_f32_e32 v150, v86, v86
	v_fmac_f32_e32 v151, v88, v88
	v_add_f32_e32 v152, v150, v151
	v_add_f32_e32 v161, v161, v152
	v_cvt_pk_f16_f32 v180, v86, v87
	v_cvt_pk_f16_f32 v181, v88, v89
	v_mul_f32_e32 v150, v91, v91
	v_mul_f32_e32 v151, v93, v93
	v_fmac_f32_e32 v150, v90, v90
	v_fmac_f32_e32 v151, v92, v92
	v_add_f32_e32 v152, v150, v151
	v_add_f32_e32 v161, v161, v152
	v_cvt_pk_f16_f32 v182, v90, v91
	v_cvt_pk_f16_f32 v183, v92, v93
	v_mul_f32_e32 v150, v95, v95
	v_mul_f32_e32 v151, v97, v97
	v_fmac_f32_e32 v150, v94, v94
	v_fmac_f32_e32 v151, v96, v96
	v_add_f32_e32 v152, v150, v151
	v_add_f32_e32 v161, v161, v152
	v_cvt_pk_f16_f32 v184, v94, v95
	v_cvt_pk_f16_f32 v185, v96, v97
	global_store_dwordx2 v145, v[178:179], s[10:11]
	global_store_dwordx2 v145, v[180:181], s[10:11] offset:512
	global_store_dwordx2 v145, v[182:183], s[10:11] offset:1024
	global_store_dwordx2 v145, v[184:185], s[10:11] offset:1536
	v_mul_f32_e32 v150, v99, v99
	v_mul_f32_e32 v151, v101, v101
	v_fmac_f32_e32 v150, v98, v98
	v_fmac_f32_e32 v151, v100, v100
	v_add_f32_e32 v162, v150, v151
	v_cvt_pk_f16_f32 v170, v98, v99
	v_cvt_pk_f16_f32 v171, v100, v101
	v_mul_f32_e32 v150, v103, v103
	v_mul_f32_e32 v151, v105, v105
	v_fmac_f32_e32 v150, v102, v102
	v_fmac_f32_e32 v151, v104, v104
	v_add_f32_e32 v152, v150, v151
	v_add_f32_e32 v162, v162, v152
	v_cvt_pk_f16_f32 v172, v102, v103
	v_cvt_pk_f16_f32 v173, v104, v105
	v_mul_f32_e32 v150, v107, v107
	v_mul_f32_e32 v151, v109, v109
	v_fmac_f32_e32 v150, v106, v106
	v_fmac_f32_e32 v151, v108, v108
	v_add_f32_e32 v152, v150, v151
	v_add_f32_e32 v162, v162, v152
	v_cvt_pk_f16_f32 v174, v106, v107
	v_cvt_pk_f16_f32 v175, v108, v109
	v_mul_f32_e32 v150, v111, v111
	v_mul_f32_e32 v151, v113, v113
	v_fmac_f32_e32 v150, v110, v110
	v_fmac_f32_e32 v151, v112, v112
	v_add_f32_e32 v152, v150, v151
	v_add_f32_e32 v162, v162, v152
	v_cvt_pk_f16_f32 v176, v110, v111
	v_cvt_pk_f16_f32 v177, v112, v113
	global_store_dwordx2 v146, v[170:171], s[10:11]
	global_store_dwordx2 v146, v[172:173], s[10:11] offset:512
	global_store_dwordx2 v146, v[174:175], s[10:11] offset:1024
	global_store_dwordx2 v146, v[176:177], s[10:11] offset:1536
	v_mul_f32_e32 v150, v115, v115
	v_mul_f32_e32 v151, v117, v117
	v_fmac_f32_e32 v150, v114, v114
	v_fmac_f32_e32 v151, v116, v116
	v_add_f32_e32 v163, v150, v151
	v_cvt_pk_f16_f32 v178, v114, v115
	v_cvt_pk_f16_f32 v179, v116, v117
	v_mul_f32_e32 v150, v119, v119
	v_mul_f32_e32 v151, v121, v121
	v_fmac_f32_e32 v150, v118, v118
	v_fmac_f32_e32 v151, v120, v120
	v_add_f32_e32 v152, v150, v151
	v_add_f32_e32 v163, v163, v152
	v_cvt_pk_f16_f32 v180, v118, v119
	v_cvt_pk_f16_f32 v181, v120, v121
	v_mul_f32_e32 v150, v123, v123
	v_mul_f32_e32 v151, v125, v125
	v_fmac_f32_e32 v150, v122, v122
	v_fmac_f32_e32 v151, v124, v124
	v_add_f32_e32 v152, v150, v151
	v_add_f32_e32 v163, v163, v152
	v_cvt_pk_f16_f32 v182, v122, v123
	v_cvt_pk_f16_f32 v183, v124, v125
	v_mul_f32_e32 v150, v127, v127
	v_mul_f32_e32 v151, v129, v129
	v_fmac_f32_e32 v150, v126, v126
	v_fmac_f32_e32 v151, v128, v128
	v_add_f32_e32 v152, v150, v151
	v_add_f32_e32 v163, v163, v152
	v_cvt_pk_f16_f32 v184, v126, v127
	v_cvt_pk_f16_f32 v185, v128, v129
	global_store_dwordx2 v147, v[178:179], s[10:11]
	global_store_dwordx2 v147, v[180:181], s[10:11] offset:512
	global_store_dwordx2 v147, v[182:183], s[10:11] offset:1024
	global_store_dwordx2 v147, v[184:185], s[10:11] offset:1536
	ds_bpermute_b32 v164, v130, v160
	ds_bpermute_b32 v165, v130, v161
	ds_bpermute_b32 v166, v130, v162
	ds_bpermute_b32 v167, v130, v163
	s_waitcnt lgkmcnt(0)
	v_add_f32_e32 v160, v160, v164
	v_add_f32_e32 v161, v161, v165
	v_add_f32_e32 v162, v162, v166
	v_add_f32_e32 v163, v163, v167
	ds_bpermute_b32 v164, v131, v160
	ds_bpermute_b32 v165, v131, v161
	ds_bpermute_b32 v166, v131, v162
	ds_bpermute_b32 v167, v131, v163
	s_waitcnt lgkmcnt(0)
; __device__ void p0_xconv(const Args& a) {
;     ...
;     for (int row0 = (int)blockIdx.x * 8 + wv; row0 < MROWS; row0 += 4 * nwv) {
;         f32x4 v[4][4];
; #pragma unroll
;         for (int r = 0; r < 4; ++r) {
;             const int row = row0 + r * nwv;
;             if (row < MROWS) {
;                 const float* src = (row < ROWS_PROMPT) ? a.x_prompt + (size_t)row * DM : a.x_sample + (size_t)(row - ROWS_PROMPT) * DM;
; #pragma unroll
;                 for (int i = 0; i < 4; ++i) v[r][i] = __builtin_nontemporal_load((const f32x4*)(src + i * 256 + lane * 4));
;             }
;         }
; #pragma unroll
;         for (int r = 0; r < 4; ++r) {
;             const int row = row0 + r * nwv;
;             if (row < MROWS) {
;                 float ss = 0.f;
; #pragma unroll
;                 for (int i = 0; i < 4; ++i) {
;                     const f32x4 x = v[r][i];
;                     ss += (x[0] * x[0] + x[1] * x[1]) + (x[2] * x[2] + x[3] * x[3]);
;                     f16x4 h; h[0] = (f16)x[0]; h[1] = (f16)x[1]; h[2] = (f16)x[2]; h[3] = (f16)x[3];
;                     *(f16x4*)(XH + (size_t)row * DM + i * 256 + lane * 4) = h;
;                 }
; #pragma unroll
;                 for (int o = 1; o < 64; o <<= 1) ss += __shfl_xor(ss, o);
;                 if (lane < 16) SS[(size_t)row * 16 + lane] = (lane == 0) ? ss : 0.f;
	v_add_f32_e32 v160, v160, v164
	v_add_f32_e32 v161, v161, v165
	v_add_f32_e32 v162, v162, v166
	v_add_f32_e32 v163, v163, v167
	ds_bpermute_b32 v164, v132, v160
	ds_bpermute_b32 v165, v132, v161
	ds_bpermute_b32 v166, v132, v162
	ds_bpermute_b32 v167, v132, v163
	s_waitcnt lgkmcnt(0)
	v_add_f32_e32 v160, v160, v164
	v_add_f32_e32 v161, v161, v165
	v_add_f32_e32 v162, v162, v166
	v_add_f32_e32 v163, v163, v167
	ds_bpermute_b32 v164, v133, v160
	ds_bpermute_b32 v165, v133, v161
	ds_bpermute_b32 v166, v133, v162
	ds_bpermute_b32 v167, v133, v163
	s_waitcnt lgkmcnt(0)
	v_add_f32_e32 v160, v160, v164
	v_add_f32_e32 v161, v161, v165
	v_add_f32_e32 v162, v162, v166
	v_add_f32_e32 v163, v163, v167
	ds_bpermute_b32 v164, v134, v160
	ds_bpermute_b32 v165, v134, v161
	ds_bpermute_b32 v166, v134, v162
	ds_bpermute_b32 v167, v134, v163
	s_waitcnt lgkmcnt(0)
	v_add_f32_e32 v160, v160, v164
	v_add_f32_e32 v161, v161, v165
	v_add_f32_e32 v162, v162, v166
	v_add_f32_e32 v163, v163, v167
	ds_bpermute_b32 v164, v135, v160
	ds_bpermute_b32 v165, v135, v161
	ds_bpermute_b32 v166, v135, v162
	ds_bpermute_b32 v167, v135, v163
	s_waitcnt lgkmcnt(0)
	v_add_f32_e32 v160, v160, v164
	v_add_f32_e32 v161, v161, v165
	v_add_f32_e32 v162, v162, v166
	v_add_f32_e32 v163, v163, v167
	v_cndmask_b32_e64 v164, 0, v160, s[12:13]
	v_cndmask_b32_e64 v165, 0, v161, s[12:13]
	v_cndmask_b32_e64 v166, 0, v162, s[12:13]
	v_cndmask_b32_e64 v167, 0, v163, s[12:13]
	s_mov_b64 exec, 0xffff
	global_store_dword v186, v164, s[6:7]
	global_store_dword v187, v165, s[6:7]
	global_store_dword v188, v166, s[6:7]
	global_store_dword v189, v167, s[6:7]
	s_mov_b64 exec, -1
	s_add_i32 s6, s3, 0x3000
	s_lshl_b32 s6, s6, 12
	s_add_u32 s4, s18, s6
	s_addc_u32 s5, s19, 0
	global_load_dwordx4 v[66:69], v140, s[4:5] nt
	global_load_dwordx4 v[70:73], v140, s[4:5] offset:1024 nt
	global_load_dwordx4 v[74:77], v140, s[4:5] offset:2048 nt
	global_load_dwordx4 v[78:81], v140, s[4:5] offset:3072 nt
	global_load_dwordx4 v[82:85], v141, s[4:5] nt
	global_load_dwordx4 v[86:89], v141, s[4:5] offset:1024 nt
	global_load_dwordx4 v[90:93], v141, s[4:5] offset:2048 nt
	global_load_dwordx4 v[94:97], v141, s[4:5] offset:3072 nt
	global_load_dwordx4 v[98:101], v142, s[4:5] nt
	global_load_dwordx4 v[102:105], v142, s[4:5] offset:1024 nt
	global_load_dwordx4 v[106:109], v142, s[4:5] offset:2048 nt
	global_load_dwordx4 v[110:113], v142, s[4:5] offset:3072 nt
	global_load_dwordx4 v[114:117], v143, s[4:5] nt
	global_load_dwordx4 v[118:121], v143, s[4:5] offset:1024 nt
	global_load_dwordx4 v[122:125], v143, s[4:5] offset:2048 nt
	global_load_dwordx4 v[126:129], v143, s[4:5] offset:3072 nt
	s_waitcnt vmcnt(36)
	s_add_i32 s6, s3, 0x6000
	s_lshl_b32 s7, s6, 11
	s_add_u32 s10, s40, s7
	s_addc_u32 s11, s41, 0
	s_lshl_b32 s7, s6, 6
	s_add_u32 s6, s40, s7
	s_addc_u32 s7, s41, 0
	s_add_u32 s6, s6, 0x1f800000
	s_addc_u32 s7, s7, 0
	v_mul_f32_e32 v150, v3, v3
	v_mul_f32_e32 v151, v5, v5
	v_fmac_f32_e32 v150, v2, v2
	v_fmac_f32_e32 v151, v4, v4
	v_add_f32_e32 v160, v150, v151
	v_cvt_pk_f16_f32 v170, v2, v3
	v_cvt_pk_f16_f32 v171, v4, v5
	v_mul_f32_e32 v150, v7, v7
	v_mul_f32_e32 v151, v9, v9
	v_fmac_f32_e32 v150, v6, v6
	v_fmac_f32_e32 v151, v8, v8
	v_add_f32_e32 v152, v150, v151
	v_add_f32_e32 v160, v160, v152
	v_cvt_pk_f16_f32 v172, v6, v7
	v_cvt_pk_f16_f32 v173, v8, v9
	v_mul_f32_e32 v150, v11, v11
	v_mul_f32_e32 v151, v13, v13
	v_fmac_f32_e32 v150, v10, v10
	v_fmac_f32_e32 v151, v12, v12
	v_add_f32_e32 v152, v150, v151
	v_add_f32_e32 v160, v160, v152
	v_cvt_pk_f16_f32 v174, v10, v11
	v_cvt_pk_f16_f32 v175, v12, v13
	v_mul_f32_e32 v150, v15, v15
	v_mul_f32_e32 v151, v17, v17
	v_fmac_f32_e32 v150, v14, v14
	v_fmac_f32_e32 v151, v16, v16
	v_add_f32_e32 v152, v150, v151
	v_add_f32_e32 v160, v160, v152
	v_cvt_pk_f16_f32 v176, v14, v15
	v_cvt_pk_f16_f32 v177, v16, v17
	global_store_dwordx2 v144, v[170:171], s[10:11]
	global_store_dwordx2 v144, v[172:173], s[10:11] offset:512
	global_store_dwordx2 v144, v[174:175], s[10:11] offset:1024
	global_store_dwordx2 v144, v[176:177], s[10:11] offset:1536
	v_mul_f32_e32 v150, v19, v19
	v_mul_f32_e32 v151, v21, v21
	v_fmac_f32_e32 v150, v18, v18
	v_fmac_f32_e32 v151, v20, v20
	v_add_f32_e32 v161, v150, v151
	v_cvt_pk_f16_f32 v178, v18, v19
	v_cvt_pk_f16_f32 v179, v20, v21
	v_mul_f32_e32 v150, v23, v23
	v_mul_f32_e32 v151, v25, v25
	v_fmac_f32_e32 v150, v22, v22
	v_fmac_f32_e32 v151, v24, v24
	v_add_f32_e32 v152, v150, v151
	v_add_f32_e32 v161, v161, v152
	v_cvt_pk_f16_f32 v180, v22, v23
	v_cvt_pk_f16_f32 v181, v24, v25
	v_mul_f32_e32 v150, v27, v27
	v_mul_f32_e32 v151, v29, v29
	v_fmac_f32_e32 v150, v26, v26
	v_fmac_f32_e32 v151, v28, v28
	v_add_f32_e32 v152, v150, v151
	v_add_f32_e32 v161, v161, v152
	v_cvt_pk_f16_f32 v182, v26, v27
	v_cvt_pk_f16_f32 v183, v28, v29
	v_mul_f32_e32 v150, v31, v31
	v_mul_f32_e32 v151, v33, v33
	v_fmac_f32_e32 v150, v30, v30
	v_fmac_f32_e32 v151, v32, v32
	v_add_f32_e32 v152, v150, v151
	v_add_f32_e32 v161, v161, v152
	v_cvt_pk_f16_f32 v184, v30, v31
	v_cvt_pk_f16_f32 v185, v32, v33
	global_store_dwordx2 v145, v[178:179], s[10:11]
	global_store_dwordx2 v145, v[180:181], s[10:11] offset:512
	global_store_dwordx2 v145, v[182:183], s[10:11] offset:1024
	global_store_dwordx2 v145, v[184:185], s[10:11] offset:1536
	v_mul_f32_e32 v150, v35, v35
	v_mul_f32_e32 v151, v37, v37
	v_fmac_f32_e32 v150, v34, v34
	v_fmac_f32_e32 v151, v36, v36
	v_add_f32_e32 v162, v150, v151
	v_cvt_pk_f16_f32 v170, v34, v35
	v_cvt_pk_f16_f32 v171, v36, v37
	v_mul_f32_e32 v150, v39, v39
	v_mul_f32_e32 v151, v41, v41
	v_fmac_f32_e32 v150, v38, v38
	v_fmac_f32_e32 v151, v40, v40
	v_add_f32_e32 v152, v150, v151
; __device__ void p0_xconv(const Args& a) {
;     ...
;     for (int row0 = (int)blockIdx.x * 8 + wv; row0 < MROWS; row0 += 4 * nwv) {
;         f32x4 v[4][4];
; #pragma unroll
;         for (int r = 0; r < 4; ++r) {
;             const int row = row0 + r * nwv;
;             if (row < MROWS) {
;                 const float* src = (row < ROWS_PROMPT) ? a.x_prompt + (size_t)row * DM : a.x_sample + (size_t)(row - ROWS_PROMPT) * DM;
; #pragma unroll
;                 for (int i = 0; i < 4; ++i) v[r][i] = __builtin_nontemporal_load((const f32x4*)(src + i * 256 + lane * 4));
;             }
;         }
; #pragma unroll
;         for (int r = 0; r < 4; ++r) {
;             const int row = row0 + r * nwv;
;             if (row < MROWS) {
;                 float ss = 0.f;
; #pragma unroll
;                 for (int i = 0; i < 4; ++i) {
;                     const f32x4 x = v[r][i];
;                     ss += (x[0] * x[0] + x[1] * x[1]) + (x[2] * x[2] + x[3] * x[3]);
;                     f16x4 h; h[0] = (f16)x[0]; h[1] = (f16)x[1]; h[2] = (f16)x[2]; h[3] = (f16)x[3];
;                     *(f16x4*)(XH + (size_t)row * DM + i * 256 + lane * 4) = h;
;                 }
; #pragma unroll
;                 for (int o = 1; o < 64; o <<= 1) ss += __shfl_xor(ss, o);
;                 if (lane < 16) SS[(size_t)row * 16 + lane] = (lane == 0) ? ss : 0.f;
	v_add_f32_e32 v162, v162, v152
	v_cvt_pk_f16_f32 v172, v38, v39
	v_cvt_pk_f16_f32 v173, v40, v41
	v_mul_f32_e32 v150, v43, v43
	v_mul_f32_e32 v151, v45, v45
	v_fmac_f32_e32 v150, v42, v42
	v_fmac_f32_e32 v151, v44, v44
	v_add_f32_e32 v152, v150, v151
	v_add_f32_e32 v162, v162, v152
	v_cvt_pk_f16_f32 v174, v42, v43
	v_cvt_pk_f16_f32 v175, v44, v45
	v_mul_f32_e32 v150, v47, v47
	v_mul_f32_e32 v151, v49, v49
	v_fmac_f32_e32 v150, v46, v46
	v_fmac_f32_e32 v151, v48, v48
	v_add_f32_e32 v152, v150, v151
	v_add_f32_e32 v162, v162, v152
	v_cvt_pk_f16_f32 v176, v46, v47
	v_cvt_pk_f16_f32 v177, v48, v49
	global_store_dwordx2 v146, v[170:171], s[10:11]
	global_store_dwordx2 v146, v[172:173], s[10:11] offset:512
	global_store_dwordx2 v146, v[174:175], s[10:11] offset:1024
	global_store_dwordx2 v146, v[176:177], s[10:11] offset:1536
	v_mul_f32_e32 v150, v51, v51
	v_mul_f32_e32 v151, v53, v53
	v_fmac_f32_e32 v150, v50, v50
	v_fmac_f32_e32 v151, v52, v52
	v_add_f32_e32 v163, v150, v151
	v_cvt_pk_f16_f32 v178, v50, v51
	v_cvt_pk_f16_f32 v179, v52, v53
	v_mul_f32_e32 v150, v55, v55
	v_mul_f32_e32 v151, v57, v57
	v_fmac_f32_e32 v150, v54, v54
	v_fmac_f32_e32 v151, v56, v56
	v_add_f32_e32 v152, v150, v151
	v_add_f32_e32 v163, v163, v152
	v_cvt_pk_f16_f32 v180, v54, v55
	v_cvt_pk_f16_f32 v181, v56, v57
	v_mul_f32_e32 v150, v59, v59
	v_mul_f32_e32 v151, v61, v61
	v_fmac_f32_e32 v150, v58, v58
	v_fmac_f32_e32 v151, v60, v60
	v_add_f32_e32 v152, v150, v151
	v_add_f32_e32 v163, v163, v152
	v_cvt_pk_f16_f32 v182, v58, v59
	v_cvt_pk_f16_f32 v183, v60, v61
	v_mul_f32_e32 v150, v63, v63
	v_mul_f32_e32 v151, v65, v65
	v_fmac_f32_e32 v150, v62, v62
	v_fmac_f32_e32 v151, v64, v64
	v_add_f32_e32 v152, v150, v151
	v_add_f32_e32 v163, v163, v152
	v_cvt_pk_f16_f32 v184, v62, v63
	v_cvt_pk_f16_f32 v185, v64, v65
	global_store_dwordx2 v147, v[178:179], s[10:11]
	global_store_dwordx2 v147, v[180:181], s[10:11] offset:512
	global_store_dwordx2 v147, v[182:183], s[10:11] offset:1024
	global_store_dwordx2 v147, v[184:185], s[10:11] offset:1536
	ds_bpermute_b32 v164, v130, v160
	ds_bpermute_b32 v165, v130, v161
	ds_bpermute_b32 v166, v130, v162
	ds_bpermute_b32 v167, v130, v163
	s_waitcnt lgkmcnt(0)
	v_add_f32_e32 v160, v160, v164
	v_add_f32_e32 v161, v161, v165
	v_add_f32_e32 v162, v162, v166
	v_add_f32_e32 v163, v163, v167
	ds_bpermute_b32 v164, v131, v160
	ds_bpermute_b32 v165, v131, v161
	ds_bpermute_b32 v166, v131, v162
	ds_bpermute_b32 v167, v131, v163
	s_waitcnt lgkmcnt(0)
	v_add_f32_e32 v160, v160, v164
	v_add_f32_e32 v161, v161, v165
	v_add_f32_e32 v162, v162, v166
	v_add_f32_e32 v163, v163, v167
	ds_bpermute_b32 v164, v132, v160
	ds_bpermute_b32 v165, v132, v161
	ds_bpermute_b32 v166, v132, v162
	ds_bpermute_b32 v167, v132, v163
	s_waitcnt lgkmcnt(0)
	v_add_f32_e32 v160, v160, v164
	v_add_f32_e32 v161, v161, v165
	v_add_f32_e32 v162, v162, v166
	v_add_f32_e32 v163, v163, v167
	ds_bpermute_b32 v164, v133, v160
	ds_bpermute_b32 v165, v133, v161
	ds_bpermute_b32 v166, v133, v162
	ds_bpermute_b32 v167, v133, v163
	s_waitcnt lgkmcnt(0)
	v_add_f32_e32 v160, v160, v164
	v_add_f32_e32 v161, v161, v165
	v_add_f32_e32 v162, v162, v166
	v_add_f32_e32 v163, v163, v167
	ds_bpermute_b32 v164, v134, v160
	ds_bpermute_b32 v165, v134, v161
	ds_bpermute_b32 v166, v134, v162
	ds_bpermute_b32 v167, v134, v163
	s_waitcnt lgkmcnt(0)
	v_add_f32_e32 v160, v160, v164
	v_add_f32_e32 v161, v161, v165
	v_add_f32_e32 v162, v162, v166
	v_add_f32_e32 v163, v163, v167
	ds_bpermute_b32 v164, v135, v160
	ds_bpermute_b32 v165, v135, v161
	ds_bpermute_b32 v166, v135, v162
	ds_bpermute_b32 v167, v135, v163
	s_waitcnt lgkmcnt(0)
	v_add_f32_e32 v160, v160, v164
	v_add_f32_e32 v161, v161, v165
	v_add_f32_e32 v162, v162, v166
	v_add_f32_e32 v163, v163, v167
	v_cndmask_b32_e64 v164, 0, v160, s[12:13]
	v_cndmask_b32_e64 v165, 0, v161, s[12:13]
	v_cndmask_b32_e64 v166, 0, v162, s[12:13]
	v_cndmask_b32_e64 v167, 0, v163, s[12:13]
	s_mov_b64 exec, 0xffff
	global_store_dword v186, v164, s[6:7]
	global_store_dword v187, v165, s[6:7]
	global_store_dword v188, v166, s[6:7]
	global_store_dword v189, v167, s[6:7]
	s_mov_b64 exec, -1
	s_add_i32 s6, s3, 0x4000
	s_lshl_b32 s6, s6, 12
	s_add_u32 s4, s18, s6
	s_addc_u32 s5, s19, 0
	global_load_dwordx4 v[2:5], v140, s[4:5] nt
	global_load_dwordx4 v[6:9], v140, s[4:5] offset:1024 nt
	global_load_dwordx4 v[10:13], v140, s[4:5] offset:2048 nt
	global_load_dwordx4 v[14:17], v140, s[4:5] offset:3072 nt
	global_load_dwordx4 v[18:21], v141, s[4:5] nt
	global_load_dwordx4 v[22:25], v141, s[4:5] offset:1024 nt
	global_load_dwordx4 v[26:29], v141, s[4:5] offset:2048 nt
	global_load_dwordx4 v[30:33], v141, s[4:5] offset:3072 nt
	global_load_dwordx4 v[34:37], v142, s[4:5] nt
	global_load_dwordx4 v[38:41], v142, s[4:5] offset:1024 nt
	global_load_dwordx4 v[42:45], v142, s[4:5] offset:2048 nt
	global_load_dwordx4 v[46:49], v142, s[4:5] offset:3072 nt
	global_load_dwordx4 v[50:53], v143, s[4:5] nt
	global_load_dwordx4 v[54:57], v143, s[4:5] offset:1024 nt
	global_load_dwordx4 v[58:61], v143, s[4:5] offset:2048 nt
	global_load_dwordx4 v[62:65], v143, s[4:5] offset:3072 nt
	s_waitcnt vmcnt(36)
; __device__ void p0_xconv(const Args& a) {
;     ...
;             if (row < MROWS) {
;                 const float* src = (row < ROWS_PROMPT) ? a.x_prompt + (size_t)row * DM : a.x_sample + (size_t)(row - ROWS_PROMPT) * DM;
; #pragma unroll
;                 for (int i = 0; i < 4; ++i) v[r][i] = __builtin_nontemporal_load((const f32x4*)(src + i * 256 + lane * 4));
;             }
;         }
; #pragma unroll
;         for (int r = 0; r < 4; ++r) {
;             const int row = row0 + r * nwv;
;             if (row < MROWS) {
;                 float ss = 0.f;
; #pragma unroll
;                 for (int i = 0; i < 4; ++i) {
;                     const f32x4 x = v[r][i];
;                     ss += (x[0] * x[0] + x[1] * x[1]) + (x[2] * x[2] + x[3] * x[3]);
;                     f16x4 h; h[0] = (f16)x[0]; h[1] = (f16)x[1]; h[2] = (f16)x[2]; h[3] = (f16)x[3];
;                     *(f16x4*)(XH + (size_t)row * DM + i * 256 + lane * 4) = h;
;                 }
; #pragma unroll
;                 for (int o = 1; o < 64; o <<= 1) ss += __shfl_xor(ss, o);
	s_add_i32 s6, s3, 0x7000
	s_lshl_b32 s7, s6, 11
	s_add_u32 s10, s40, s7
	s_addc_u32 s11, s41, 0
	s_lshl_b32 s7, s6, 6
	s_add_u32 s6, s40, s7
	s_addc_u32 s7, s41, 0
	s_add_u32 s6, s6, 0x1f800000
	s_addc_u32 s7, s7, 0
	v_mul_f32_e32 v150, v67, v67
	v_mul_f32_e32 v151, v69, v69
	v_fmac_f32_e32 v150, v66, v66
	v_fmac_f32_e32 v151, v68, v68
	v_add_f32_e32 v160, v150, v151
	v_cvt_pk_f16_f32 v170, v66, v67
	v_cvt_pk_f16_f32 v171, v68, v69
	v_mul_f32_e32 v150, v71, v71
	v_mul_f32_e32 v151, v73, v73
	v_fmac_f32_e32 v150, v70, v70
	v_fmac_f32_e32 v151, v72, v72
	v_add_f32_e32 v152, v150, v151
	v_add_f32_e32 v160, v160, v152
	v_cvt_pk_f16_f32 v172, v70, v71
	v_cvt_pk_f16_f32 v173, v72, v73
	v_mul_f32_e32 v150, v75, v75
	v_mul_f32_e32 v151, v77, v77
	v_fmac_f32_e32 v150, v74, v74
	v_fmac_f32_e32 v151, v76, v76
	v_add_f32_e32 v152, v150, v151
	v_add_f32_e32 v160, v160, v152
	v_cvt_pk_f16_f32 v174, v74, v75
	v_cvt_pk_f16_f32 v175, v76, v77
	v_mul_f32_e32 v150, v79, v79
	v_mul_f32_e32 v151, v81, v81
	v_fmac_f32_e32 v150, v78, v78
	v_fmac_f32_e32 v151, v80, v80
	v_add_f32_e32 v152, v150, v151
	v_add_f32_e32 v160, v160, v152
	v_cvt_pk_f16_f32 v176, v78, v79
	v_cvt_pk_f16_f32 v177, v80, v81
	global_store_dwordx2 v144, v[170:171], s[10:11]
	global_store_dwordx2 v144, v[172:173], s[10:11] offset:512
	global_store_dwordx2 v144, v[174:175], s[10:11] offset:1024
	global_store_dwordx2 v144, v[176:177], s[10:11] offset:1536
	v_mul_f32_e32 v150, v83, v83
	v_mul_f32_e32 v151, v85, v85
	v_fmac_f32_e32 v150, v82, v82
	v_fmac_f32_e32 v151, v84, v84
	v_add_f32_e32 v161, v150, v151
	v_cvt_pk_f16_f32 v178, v82, v83
	v_cvt_pk_f16_f32 v179, v84, v85
	v_mul_f32_e32 v150, v87, v87
	v_mul_f32_e32 v151, v89, v89
	v_fmac_f32_e32 v150, v86, v86
	v_fmac_f32_e32 v151, v88, v88
	v_add_f32_e32 v152, v150, v151
	v_add_f32_e32 v161, v161, v152
	v_cvt_pk_f16_f32 v180, v86, v87
	v_cvt_pk_f16_f32 v181, v88, v89
	v_mul_f32_e32 v150, v91, v91
	v_mul_f32_e32 v151, v93, v93
	v_fmac_f32_e32 v150, v90, v90
	v_fmac_f32_e32 v151, v92, v92
	v_add_f32_e32 v152, v150, v151
	v_add_f32_e32 v161, v161, v152
	v_cvt_pk_f16_f32 v182, v90, v91
	v_cvt_pk_f16_f32 v183, v92, v93
	v_mul_f32_e32 v150, v95, v95
	v_mul_f32_e32 v151, v97, v97
	v_fmac_f32_e32 v150, v94, v94
	v_fmac_f32_e32 v151, v96, v96
	v_add_f32_e32 v152, v150, v151
	v_add_f32_e32 v161, v161, v152
	v_cvt_pk_f16_f32 v184, v94, v95
	v_cvt_pk_f16_f32 v185, v96, v97
	global_store_dwordx2 v145, v[178:179], s[10:11]
	global_store_dwordx2 v145, v[180:181], s[10:11] offset:512
	global_store_dwordx2 v145, v[182:183], s[10:11] offset:1024
	global_store_dwordx2 v145, v[184:185], s[10:11] offset:1536
	v_mul_f32_e32 v150, v99, v99
	v_mul_f32_e32 v151, v101, v101
	v_fmac_f32_e32 v150, v98, v98
	v_fmac_f32_e32 v151, v100, v100
	v_add_f32_e32 v162, v150, v151
	v_cvt_pk_f16_f32 v170, v98, v99
	v_cvt_pk_f16_f32 v171, v100, v101
	v_mul_f32_e32 v150, v103, v103
	v_mul_f32_e32 v151, v105, v105
	v_fmac_f32_e32 v150, v102, v102
	v_fmac_f32_e32 v151, v104, v104
	v_add_f32_e32 v152, v150, v151
	v_add_f32_e32 v162, v162, v152
	v_cvt_pk_f16_f32 v172, v102, v103
	v_cvt_pk_f16_f32 v173, v104, v105
	v_mul_f32_e32 v150, v107, v107
	v_mul_f32_e32 v151, v109, v109
	v_fmac_f32_e32 v150, v106, v106
	v_fmac_f32_e32 v151, v108, v108
	v_add_f32_e32 v152, v150, v151
	v_add_f32_e32 v162, v162, v152
	v_cvt_pk_f16_f32 v174, v106, v107
	v_cvt_pk_f16_f32 v175, v108, v109
	v_mul_f32_e32 v150, v111, v111
	v_mul_f32_e32 v151, v113, v113
	v_fmac_f32_e32 v150, v110, v110
	v_fmac_f32_e32 v151, v112, v112
	v_add_f32_e32 v152, v150, v151
	v_add_f32_e32 v162, v162, v152
	v_cvt_pk_f16_f32 v176, v110, v111
	v_cvt_pk_f16_f32 v177, v112, v113
	global_store_dwordx2 v146, v[170:171], s[10:11]
	global_store_dwordx2 v146, v[172:173], s[10:11] offset:512
	global_store_dwordx2 v146, v[174:175], s[10:11] offset:1024
	global_store_dwordx2 v146, v[176:177], s[10:11] offset:1536
	v_mul_f32_e32 v150, v115, v115
	v_mul_f32_e32 v151, v117, v117
	v_fmac_f32_e32 v150, v114, v114
	v_fmac_f32_e32 v151, v116, v116
	v_add_f32_e32 v163, v150, v151
	v_cvt_pk_f16_f32 v178, v114, v115
	v_cvt_pk_f16_f32 v179, v116, v117
	v_mul_f32_e32 v150, v119, v119
	v_mul_f32_e32 v151, v121, v121
	v_fmac_f32_e32 v150, v118, v118
	v_fmac_f32_e32 v151, v120, v120
	v_add_f32_e32 v152, v150, v151
	v_add_f32_e32 v163, v163, v152
	v_cvt_pk_f16_f32 v180, v118, v119
	v_cvt_pk_f16_f32 v181, v120, v121
	v_mul_f32_e32 v150, v123, v123
	v_mul_f32_e32 v151, v125, v125
	v_fmac_f32_e32 v150, v122, v122
	v_fmac_f32_e32 v151, v124, v124
	v_add_f32_e32 v152, v150, v151
	v_add_f32_e32 v163, v163, v152
	v_cvt_pk_f16_f32 v182, v122, v123
	v_cvt_pk_f16_f32 v183, v124, v125
	v_mul_f32_e32 v150, v127, v127
	v_mul_f32_e32 v151, v129, v129
	v_fmac_f32_e32 v150, v126, v126
	v_fmac_f32_e32 v151, v128, v128
	v_add_f32_e32 v152, v150, v151
	v_add_f32_e32 v163, v163, v152
	v_cvt_pk_f16_f32 v184, v126, v127
	v_cvt_pk_f16_f32 v185, v128, v129
	global_store_dwordx2 v147, v[178:179], s[10:11]
	global_store_dwordx2 v147, v[180:181], s[10:11] offset:512
	global_store_dwordx2 v147, v[182:183], s[10:11] offset:1024
	global_store_dwordx2 v147, v[184:185], s[10:11] offset:1536
	ds_bpermute_b32 v164, v130, v160
	ds_bpermute_b32 v165, v130, v161
	ds_bpermute_b32 v166, v130, v162
	ds_bpermute_b32 v167, v130, v163
	s_waitcnt lgkmcnt(0)
	v_add_f32_e32 v160, v160, v164
	v_add_f32_e32 v161, v161, v165
	v_add_f32_e32 v162, v162, v166
	v_add_f32_e32 v163, v163, v167
	ds_bpermute_b32 v164, v131, v160
	ds_bpermute_b32 v165, v131, v161
	ds_bpermute_b32 v166, v131, v162
	ds_bpermute_b32 v167, v131, v163
	s_waitcnt lgkmcnt(0)
; __device__ void p0_xconv(const Args& a) {
;     ...
;     for (int row0 = (int)blockIdx.x * 8 + wv; row0 < MROWS; row0 += 4 * nwv) {
;         f32x4 v[4][4];
; #pragma unroll
;         for (int r = 0; r < 4; ++r) {
;             const int row = row0 + r * nwv;
;             if (row < MROWS) {
;                 const float* src = (row < ROWS_PROMPT) ? a.x_prompt + (size_t)row * DM : a.x_sample + (size_t)(row - ROWS_PROMPT) * DM;
; #pragma unroll
;                 for (int i = 0; i < 4; ++i) v[r][i] = __builtin_nontemporal_load((const f32x4*)(src + i * 256 + lane * 4));
;             }
;         }
; #pragma unroll
;         for (int r = 0; r < 4; ++r) {
;             const int row = row0 + r * nwv;
;             if (row < MROWS) {
;                 float ss = 0.f;
; #pragma unroll
;                 for (int i = 0; i < 4; ++i) {
;                     const f32x4 x = v[r][i];
;                     ss += (x[0] * x[0] + x[1] * x[1]) + (x[2] * x[2] + x[3] * x[3]);
;                     f16x4 h; h[0] = (f16)x[0]; h[1] = (f16)x[1]; h[2] = (f16)x[2]; h[3] = (f16)x[3];
;                     *(f16x4*)(XH + (size_t)row * DM + i * 256 + lane * 4) = h;
;                 }
; #pragma unroll
;                 for (int o = 1; o < 64; o <<= 1) ss += __shfl_xor(ss, o);
;                 if (lane < 16) SS[(size_t)row * 16 + lane] = (lane == 0) ? ss : 0.f;
	v_add_f32_e32 v160, v160, v164
	v_add_f32_e32 v161, v161, v165
	v_add_f32_e32 v162, v162, v166
	v_add_f32_e32 v163, v163, v167
	ds_bpermute_b32 v164, v132, v160
	ds_bpermute_b32 v165, v132, v161
	ds_bpermute_b32 v166, v132, v162
	ds_bpermute_b32 v167, v132, v163
	s_waitcnt lgkmcnt(0)
	v_add_f32_e32 v160, v160, v164
	v_add_f32_e32 v161, v161, v165
	v_add_f32_e32 v162, v162, v166
	v_add_f32_e32 v163, v163, v167
	ds_bpermute_b32 v164, v133, v160
	ds_bpermute_b32 v165, v133, v161
	ds_bpermute_b32 v166, v133, v162
	ds_bpermute_b32 v167, v133, v163
	s_waitcnt lgkmcnt(0)
	v_add_f32_e32 v160, v160, v164
	v_add_f32_e32 v161, v161, v165
	v_add_f32_e32 v162, v162, v166
	v_add_f32_e32 v163, v163, v167
	ds_bpermute_b32 v164, v134, v160
	ds_bpermute_b32 v165, v134, v161
	ds_bpermute_b32 v166, v134, v162
	ds_bpermute_b32 v167, v134, v163
	s_waitcnt lgkmcnt(0)
	v_add_f32_e32 v160, v160, v164
	v_add_f32_e32 v161, v161, v165
	v_add_f32_e32 v162, v162, v166
	v_add_f32_e32 v163, v163, v167
	ds_bpermute_b32 v164, v135, v160
	ds_bpermute_b32 v165, v135, v161
	ds_bpermute_b32 v166, v135, v162
	ds_bpermute_b32 v167, v135, v163
	s_waitcnt lgkmcnt(0)
	v_add_f32_e32 v160, v160, v164
	v_add_f32_e32 v161, v161, v165
	v_add_f32_e32 v162, v162, v166
	v_add_f32_e32 v163, v163, v167
	v_cndmask_b32_e64 v164, 0, v160, s[12:13]
	v_cndmask_b32_e64 v165, 0, v161, s[12:13]
	v_cndmask_b32_e64 v166, 0, v162, s[12:13]
	v_cndmask_b32_e64 v167, 0, v163, s[12:13]
	s_mov_b64 exec, 0xffff
	global_store_dword v186, v164, s[6:7]
	global_store_dword v187, v165, s[6:7]
	global_store_dword v188, v166, s[6:7]
	global_store_dword v189, v167, s[6:7]
	s_mov_b64 exec, -1
	s_add_i32 s6, s3, 0x5000
	s_lshl_b32 s6, s6, 12
	s_add_u32 s4, s18, s6
	s_addc_u32 s5, s19, 0
	global_load_dwordx4 v[66:69], v140, s[4:5] nt
	global_load_dwordx4 v[70:73], v140, s[4:5] offset:1024 nt
	global_load_dwordx4 v[74:77], v140, s[4:5] offset:2048 nt
	global_load_dwordx4 v[78:81], v140, s[4:5] offset:3072 nt
	global_load_dwordx4 v[82:85], v141, s[4:5] nt
	global_load_dwordx4 v[86:89], v141, s[4:5] offset:1024 nt
	global_load_dwordx4 v[90:93], v141, s[4:5] offset:2048 nt
	global_load_dwordx4 v[94:97], v141, s[4:5] offset:3072 nt
	global_load_dwordx4 v[98:101], v142, s[4:5] nt
	global_load_dwordx4 v[102:105], v142, s[4:5] offset:1024 nt
	global_load_dwordx4 v[106:109], v142, s[4:5] offset:2048 nt
	global_load_dwordx4 v[110:113], v142, s[4:5] offset:3072 nt
	global_load_dwordx4 v[114:117], v143, s[4:5] nt
	global_load_dwordx4 v[118:121], v143, s[4:5] offset:1024 nt
	global_load_dwordx4 v[122:125], v143, s[4:5] offset:2048 nt
	global_load_dwordx4 v[126:129], v143, s[4:5] offset:3072 nt
	s_waitcnt vmcnt(36)
	s_add_i32 s6, s3, 0x8000
	s_lshl_b32 s7, s6, 11
	s_add_u32 s10, s40, s7
	s_addc_u32 s11, s41, 0
	s_lshl_b32 s7, s6, 6
	s_add_u32 s6, s40, s7
	s_addc_u32 s7, s41, 0
	s_add_u32 s6, s6, 0x1f800000
	s_addc_u32 s7, s7, 0
	v_mul_f32_e32 v150, v3, v3
	v_mul_f32_e32 v151, v5, v5
	v_fmac_f32_e32 v150, v2, v2
	v_fmac_f32_e32 v151, v4, v4
	v_add_f32_e32 v160, v150, v151
	v_cvt_pk_f16_f32 v170, v2, v3
	v_cvt_pk_f16_f32 v171, v4, v5
	v_mul_f32_e32 v150, v7, v7
	v_mul_f32_e32 v151, v9, v9
	v_fmac_f32_e32 v150, v6, v6
	v_fmac_f32_e32 v151, v8, v8
	v_add_f32_e32 v152, v150, v151
	v_add_f32_e32 v160, v160, v152
	v_cvt_pk_f16_f32 v172, v6, v7
	v_cvt_pk_f16_f32 v173, v8, v9
	v_mul_f32_e32 v150, v11, v11
	v_mul_f32_e32 v151, v13, v13
	v_fmac_f32_e32 v150, v10, v10
	v_fmac_f32_e32 v151, v12, v12
	v_add_f32_e32 v152, v150, v151
	v_add_f32_e32 v160, v160, v152
	v_cvt_pk_f16_f32 v174, v10, v11
	v_cvt_pk_f16_f32 v175, v12, v13
	v_mul_f32_e32 v150, v15, v15
	v_mul_f32_e32 v151, v17, v17
	v_fmac_f32_e32 v150, v14, v14
	v_fmac_f32_e32 v151, v16, v16
	v_add_f32_e32 v152, v150, v151
	v_add_f32_e32 v160, v160, v152
	v_cvt_pk_f16_f32 v176, v14, v15
	v_cvt_pk_f16_f32 v177, v16, v17
	global_store_dwordx2 v144, v[170:171], s[10:11]
	global_store_dwordx2 v144, v[172:173], s[10:11] offset:512
	global_store_dwordx2 v144, v[174:175], s[10:11] offset:1024
	global_store_dwordx2 v144, v[176:177], s[10:11] offset:1536
	v_mul_f32_e32 v150, v19, v19
	v_mul_f32_e32 v151, v21, v21
	v_fmac_f32_e32 v150, v18, v18
	v_fmac_f32_e32 v151, v20, v20
	v_add_f32_e32 v161, v150, v151
	v_cvt_pk_f16_f32 v178, v18, v19
	v_cvt_pk_f16_f32 v179, v20, v21
	v_mul_f32_e32 v150, v23, v23
	v_mul_f32_e32 v151, v25, v25
	v_fmac_f32_e32 v150, v22, v22
	v_fmac_f32_e32 v151, v24, v24
	v_add_f32_e32 v152, v150, v151
	v_add_f32_e32 v161, v161, v152
	v_cvt_pk_f16_f32 v180, v22, v23
	v_cvt_pk_f16_f32 v181, v24, v25
	v_mul_f32_e32 v150, v27, v27
	v_mul_f32_e32 v151, v29, v29
	v_fmac_f32_e32 v150, v26, v26
	v_fmac_f32_e32 v151, v28, v28
	v_add_f32_e32 v152, v150, v151
	v_add_f32_e32 v161, v161, v152
	v_cvt_pk_f16_f32 v182, v26, v27
	v_cvt_pk_f16_f32 v183, v28, v29
	v_mul_f32_e32 v150, v31, v31
	v_mul_f32_e32 v151, v33, v33
	v_fmac_f32_e32 v150, v30, v30
	v_fmac_f32_e32 v151, v32, v32
	v_add_f32_e32 v152, v150, v151
	v_add_f32_e32 v161, v161, v152
	v_cvt_pk_f16_f32 v184, v30, v31
	v_cvt_pk_f16_f32 v185, v32, v33
	global_store_dwordx2 v145, v[178:179], s[10:11]
	global_store_dwordx2 v145, v[180:181], s[10:11] offset:512
	global_store_dwordx2 v145, v[182:183], s[10:11] offset:1024
	global_store_dwordx2 v145, v[184:185], s[10:11] offset:1536
	v_mul_f32_e32 v150, v35, v35
	v_mul_f32_e32 v151, v37, v37
	v_fmac_f32_e32 v150, v34, v34
	v_fmac_f32_e32 v151, v36, v36
	v_add_f32_e32 v162, v150, v151
	v_cvt_pk_f16_f32 v170, v34, v35
	v_cvt_pk_f16_f32 v171, v36, v37
	v_mul_f32_e32 v150, v39, v39
	v_mul_f32_e32 v151, v41, v41
	v_fmac_f32_e32 v150, v38, v38
	v_fmac_f32_e32 v151, v40, v40
	v_add_f32_e32 v152, v150, v151
; __device__ void p0_xconv(const Args& a) {
;     ...
;     for (int row0 = (int)blockIdx.x * 8 + wv; row0 < MROWS; row0 += 4 * nwv) {
;         f32x4 v[4][4];
; #pragma unroll
;         for (int r = 0; r < 4; ++r) {
;             const int row = row0 + r * nwv;
;             if (row < MROWS) {
;                 const float* src = (row < ROWS_PROMPT) ? a.x_prompt + (size_t)row * DM : a.x_sample + (size_t)(row - ROWS_PROMPT) * DM;
; #pragma unroll
;                 for (int i = 0; i < 4; ++i) v[r][i] = __builtin_nontemporal_load((const f32x4*)(src + i * 256 + lane * 4));
;             }
;         }
; #pragma unroll
;         for (int r = 0; r < 4; ++r) {
;             const int row = row0 + r * nwv;
;             if (row < MROWS) {
;                 float ss = 0.f;
; #pragma unroll
;                 for (int i = 0; i < 4; ++i) {
;                     const f32x4 x = v[r][i];
;                     ss += (x[0] * x[0] + x[1] * x[1]) + (x[2] * x[2] + x[3] * x[3]);
;                     f16x4 h; h[0] = (f16)x[0]; h[1] = (f16)x[1]; h[2] = (f16)x[2]; h[3] = (f16)x[3];
;                     *(f16x4*)(XH + (size_t)row * DM + i * 256 + lane * 4) = h;
;                 }
; #pragma unroll
;                 for (int o = 1; o < 64; o <<= 1) ss += __shfl_xor(ss, o);
;                 if (lane < 16) SS[(size_t)row * 16 + lane] = (lane == 0) ? ss : 0.f;
	v_add_f32_e32 v162, v162, v152
	v_cvt_pk_f16_f32 v172, v38, v39
	v_cvt_pk_f16_f32 v173, v40, v41
	v_mul_f32_e32 v150, v43, v43
	v_mul_f32_e32 v151, v45, v45
	v_fmac_f32_e32 v150, v42, v42
	v_fmac_f32_e32 v151, v44, v44
	v_add_f32_e32 v152, v150, v151
	v_add_f32_e32 v162, v162, v152
	v_cvt_pk_f16_f32 v174, v42, v43
	v_cvt_pk_f16_f32 v175, v44, v45
	v_mul_f32_e32 v150, v47, v47
	v_mul_f32_e32 v151, v49, v49
	v_fmac_f32_e32 v150, v46, v46
	v_fmac_f32_e32 v151, v48, v48
	v_add_f32_e32 v152, v150, v151
	v_add_f32_e32 v162, v162, v152
	v_cvt_pk_f16_f32 v176, v46, v47
	v_cvt_pk_f16_f32 v177, v48, v49
	global_store_dwordx2 v146, v[170:171], s[10:11]
	global_store_dwordx2 v146, v[172:173], s[10:11] offset:512
	global_store_dwordx2 v146, v[174:175], s[10:11] offset:1024
	global_store_dwordx2 v146, v[176:177], s[10:11] offset:1536
	v_mul_f32_e32 v150, v51, v51
	v_mul_f32_e32 v151, v53, v53
	v_fmac_f32_e32 v150, v50, v50
	v_fmac_f32_e32 v151, v52, v52
	v_add_f32_e32 v163, v150, v151
	v_cvt_pk_f16_f32 v178, v50, v51
	v_cvt_pk_f16_f32 v179, v52, v53
	v_mul_f32_e32 v150, v55, v55
	v_mul_f32_e32 v151, v57, v57
	v_fmac_f32_e32 v150, v54, v54
	v_fmac_f32_e32 v151, v56, v56
	v_add_f32_e32 v152, v150, v151
	v_add_f32_e32 v163, v163, v152
	v_cvt_pk_f16_f32 v180, v54, v55
	v_cvt_pk_f16_f32 v181, v56, v57
	v_mul_f32_e32 v150, v59, v59
	v_mul_f32_e32 v151, v61, v61
	v_fmac_f32_e32 v150, v58, v58
	v_fmac_f32_e32 v151, v60, v60
	v_add_f32_e32 v152, v150, v151
	v_add_f32_e32 v163, v163, v152
	v_cvt_pk_f16_f32 v182, v58, v59
	v_cvt_pk_f16_f32 v183, v60, v61
	v_mul_f32_e32 v150, v63, v63
	v_mul_f32_e32 v151, v65, v65
	v_fmac_f32_e32 v150, v62, v62
	v_fmac_f32_e32 v151, v64, v64
	v_add_f32_e32 v152, v150, v151
	v_add_f32_e32 v163, v163, v152
	v_cvt_pk_f16_f32 v184, v62, v63
	v_cvt_pk_f16_f32 v185, v64, v65
	global_store_dwordx2 v147, v[178:179], s[10:11]
	global_store_dwordx2 v147, v[180:181], s[10:11] offset:512
	global_store_dwordx2 v147, v[182:183], s[10:11] offset:1024
	global_store_dwordx2 v147, v[184:185], s[10:11] offset:1536
	ds_bpermute_b32 v164, v130, v160
	ds_bpermute_b32 v165, v130, v161
	ds_bpermute_b32 v166, v130, v162
	ds_bpermute_b32 v167, v130, v163
	s_waitcnt lgkmcnt(0)
	v_add_f32_e32 v160, v160, v164
	v_add_f32_e32 v161, v161, v165
	v_add_f32_e32 v162, v162, v166
	v_add_f32_e32 v163, v163, v167
	ds_bpermute_b32 v164, v131, v160
	ds_bpermute_b32 v165, v131, v161
	ds_bpermute_b32 v166, v131, v162
	ds_bpermute_b32 v167, v131, v163
	s_waitcnt lgkmcnt(0)
	v_add_f32_e32 v160, v160, v164
	v_add_f32_e32 v161, v161, v165
	v_add_f32_e32 v162, v162, v166
	v_add_f32_e32 v163, v163, v167
	ds_bpermute_b32 v164, v132, v160
	ds_bpermute_b32 v165, v132, v161
	ds_bpermute_b32 v166, v132, v162
	ds_bpermute_b32 v167, v132, v163
	s_waitcnt lgkmcnt(0)
	v_add_f32_e32 v160, v160, v164
	v_add_f32_e32 v161, v161, v165
	v_add_f32_e32 v162, v162, v166
	v_add_f32_e32 v163, v163, v167
	ds_bpermute_b32 v164, v133, v160
	ds_bpermute_b32 v165, v133, v161
	ds_bpermute_b32 v166, v133, v162
	ds_bpermute_b32 v167, v133, v163
	s_waitcnt lgkmcnt(0)
	v_add_f32_e32 v160, v160, v164
	v_add_f32_e32 v161, v161, v165
	v_add_f32_e32 v162, v162, v166
	v_add_f32_e32 v163, v163, v167
	ds_bpermute_b32 v164, v134, v160
	ds_bpermute_b32 v165, v134, v161
	ds_bpermute_b32 v166, v134, v162
	ds_bpermute_b32 v167, v134, v163
	s_waitcnt lgkmcnt(0)
	v_add_f32_e32 v160, v160, v164
	v_add_f32_e32 v161, v161, v165
	v_add_f32_e32 v162, v162, v166
	v_add_f32_e32 v163, v163, v167
	ds_bpermute_b32 v164, v135, v160
	ds_bpermute_b32 v165, v135, v161
	ds_bpermute_b32 v166, v135, v162
	ds_bpermute_b32 v167, v135, v163
	s_waitcnt lgkmcnt(0)
	v_add_f32_e32 v160, v160, v164
	v_add_f32_e32 v161, v161, v165
	v_add_f32_e32 v162, v162, v166
	v_add_f32_e32 v163, v163, v167
	v_cndmask_b32_e64 v164, 0, v160, s[12:13]
	v_cndmask_b32_e64 v165, 0, v161, s[12:13]
	v_cndmask_b32_e64 v166, 0, v162, s[12:13]
	v_cndmask_b32_e64 v167, 0, v163, s[12:13]
	s_mov_b64 exec, 0xffff
	global_store_dword v186, v164, s[6:7]
	global_store_dword v187, v165, s[6:7]
	global_store_dword v188, v166, s[6:7]
	global_store_dword v189, v167, s[6:7]
	s_mov_b64 exec, -1
	s_waitcnt vmcnt(20)
	s_add_i32 s6, s3, 0x9000
	s_lshl_b32 s7, s6, 11
	s_add_u32 s10, s40, s7
	s_addc_u32 s11, s41, 0
	s_lshl_b32 s7, s6, 6
	s_add_u32 s6, s40, s7
	s_addc_u32 s7, s41, 0
	s_add_u32 s6, s6, 0x1f800000
	s_addc_u32 s7, s7, 0
	v_mul_f32_e32 v150, v67, v67
	v_mul_f32_e32 v151, v69, v69
	v_fmac_f32_e32 v150, v66, v66
	v_fmac_f32_e32 v151, v68, v68
	v_add_f32_e32 v160, v150, v151
	v_cvt_pk_f16_f32 v170, v66, v67
	v_cvt_pk_f16_f32 v171, v68, v69
	v_mul_f32_e32 v150, v71, v71
	v_mul_f32_e32 v151, v73, v73
	v_fmac_f32_e32 v150, v70, v70
	v_fmac_f32_e32 v151, v72, v72
	v_add_f32_e32 v152, v150, v151
	v_add_f32_e32 v160, v160, v152
	v_cvt_pk_f16_f32 v172, v70, v71
	v_cvt_pk_f16_f32 v173, v72, v73
	v_mul_f32_e32 v150, v75, v75
	v_mul_f32_e32 v151, v77, v77
	v_fmac_f32_e32 v150, v74, v74
	v_fmac_f32_e32 v151, v76, v76
	v_add_f32_e32 v152, v150, v151
	v_add_f32_e32 v160, v160, v152
	v_cvt_pk_f16_f32 v174, v74, v75
	v_cvt_pk_f16_f32 v175, v76, v77
	v_mul_f32_e32 v150, v79, v79
	v_mul_f32_e32 v151, v81, v81
	v_fmac_f32_e32 v150, v78, v78
	v_fmac_f32_e32 v151, v80, v80
	v_add_f32_e32 v152, v150, v151
	v_add_f32_e32 v160, v160, v152
	v_cvt_pk_f16_f32 v176, v78, v79
	v_cvt_pk_f16_f32 v177, v80, v81
	global_store_dwordx2 v144, v[170:171], s[10:11]
	global_store_dwordx2 v144, v[172:173], s[10:11] offset:512
	global_store_dwordx2 v144, v[174:175], s[10:11] offset:1024
	global_store_dwordx2 v144, v[176:177], s[10:11] offset:1536
	v_mul_f32_e32 v150, v83, v83
	v_mul_f32_e32 v151, v85, v85
; __device__ void p0_xconv(const Args& a) {
;     ...
;         for (int r = 0; r < 4; ++r) {
;             const int row = row0 + r * nwv;
;             if (row < MROWS) {
;                 float ss = 0.f;
; #pragma unroll
;                 for (int i = 0; i < 4; ++i) {
;                     const f32x4 x = v[r][i];
;                     ss += (x[0] * x[0] + x[1] * x[1]) + (x[2] * x[2] + x[3] * x[3]);
;                     f16x4 h; h[0] = (f16)x[0]; h[1] = (f16)x[1]; h[2] = (f16)x[2]; h[3] = (f16)x[3];
;                     *(f16x4*)(XH + (size_t)row * DM + i * 256 + lane * 4) = h;
;                 }
; #pragma unroll
;                 for (int o = 1; o < 64; o <<= 1) ss += __shfl_xor(ss, o);
;                 if (lane < 16) SS[(size_t)row * 16 + lane] = (lane == 0) ? ss : 0.f;
	v_fmac_f32_e32 v150, v82, v82
	v_fmac_f32_e32 v151, v84, v84
	v_add_f32_e32 v161, v150, v151
	v_cvt_pk_f16_f32 v178, v82, v83
	v_cvt_pk_f16_f32 v179, v84, v85
	v_mul_f32_e32 v150, v87, v87
	v_mul_f32_e32 v151, v89, v89
	v_fmac_f32_e32 v150, v86, v86
	v_fmac_f32_e32 v151, v88, v88
	v_add_f32_e32 v152, v150, v151
	v_add_f32_e32 v161, v161, v152
	v_cvt_pk_f16_f32 v180, v86, v87
	v_cvt_pk_f16_f32 v181, v88, v89
	v_mul_f32_e32 v150, v91, v91
	v_mul_f32_e32 v151, v93, v93
	v_fmac_f32_e32 v150, v90, v90
	v_fmac_f32_e32 v151, v92, v92
	v_add_f32_e32 v152, v150, v151
	v_add_f32_e32 v161, v161, v152
	v_cvt_pk_f16_f32 v182, v90, v91
	v_cvt_pk_f16_f32 v183, v92, v93
	v_mul_f32_e32 v150, v95, v95
	v_mul_f32_e32 v151, v97, v97
	v_fmac_f32_e32 v150, v94, v94
	v_fmac_f32_e32 v151, v96, v96
	v_add_f32_e32 v152, v150, v151
	v_add_f32_e32 v161, v161, v152
	v_cvt_pk_f16_f32 v184, v94, v95
	v_cvt_pk_f16_f32 v185, v96, v97
	global_store_dwordx2 v145, v[178:179], s[10:11]
	global_store_dwordx2 v145, v[180:181], s[10:11] offset:512
	global_store_dwordx2 v145, v[182:183], s[10:11] offset:1024
	global_store_dwordx2 v145, v[184:185], s[10:11] offset:1536
	v_mul_f32_e32 v150, v99, v99
	v_mul_f32_e32 v151, v101, v101
	v_fmac_f32_e32 v150, v98, v98
	v_fmac_f32_e32 v151, v100, v100
	v_add_f32_e32 v162, v150, v151
	v_cvt_pk_f16_f32 v170, v98, v99
	v_cvt_pk_f16_f32 v171, v100, v101
	v_mul_f32_e32 v150, v103, v103
	v_mul_f32_e32 v151, v105, v105
	v_fmac_f32_e32 v150, v102, v102
	v_fmac_f32_e32 v151, v104, v104
	v_add_f32_e32 v152, v150, v151
	v_add_f32_e32 v162, v162, v152
	v_cvt_pk_f16_f32 v172, v102, v103
	v_cvt_pk_f16_f32 v173, v104, v105
	v_mul_f32_e32 v150, v107, v107
	v_mul_f32_e32 v151, v109, v109
	v_fmac_f32_e32 v150, v106, v106
	v_fmac_f32_e32 v151, v108, v108
	v_add_f32_e32 v152, v150, v151
	v_add_f32_e32 v162, v162, v152
	v_cvt_pk_f16_f32 v174, v106, v107
	v_cvt_pk_f16_f32 v175, v108, v109
	v_mul_f32_e32 v150, v111, v111
	v_mul_f32_e32 v151, v113, v113
	v_fmac_f32_e32 v150, v110, v110
	v_fmac_f32_e32 v151, v112, v112
	v_add_f32_e32 v152, v150, v151
	v_add_f32_e32 v162, v162, v152
	v_cvt_pk_f16_f32 v176, v110, v111
	v_cvt_pk_f16_f32 v177, v112, v113
	global_store_dwordx2 v146, v[170:171], s[10:11]
	global_store_dwordx2 v146, v[172:173], s[10:11] offset:512
	global_store_dwordx2 v146, v[174:175], s[10:11] offset:1024
	global_store_dwordx2 v146, v[176:177], s[10:11] offset:1536
	v_mul_f32_e32 v150, v115, v115
	v_mul_f32_e32 v151, v117, v117
	v_fmac_f32_e32 v150, v114, v114
	v_fmac_f32_e32 v151, v116, v116
	v_add_f32_e32 v163, v150, v151
	v_cvt_pk_f16_f32 v178, v114, v115
	v_cvt_pk_f16_f32 v179, v116, v117
	v_mul_f32_e32 v150, v119, v119
	v_mul_f32_e32 v151, v121, v121
	v_fmac_f32_e32 v150, v118, v118
	v_fmac_f32_e32 v151, v120, v120
	v_add_f32_e32 v152, v150, v151
	v_add_f32_e32 v163, v163, v152
	v_cvt_pk_f16_f32 v180, v118, v119
	v_cvt_pk_f16_f32 v181, v120, v121
	v_mul_f32_e32 v150, v123, v123
	v_mul_f32_e32 v151, v125, v125
	v_fmac_f32_e32 v150, v122, v122
	v_fmac_f32_e32 v151, v124, v124
	v_add_f32_e32 v152, v150, v151
	v_add_f32_e32 v163, v163, v152
	v_cvt_pk_f16_f32 v182, v122, v123
	v_cvt_pk_f16_f32 v183, v124, v125
	v_mul_f32_e32 v150, v127, v127
	v_mul_f32_e32 v151, v129, v129
	v_fmac_f32_e32 v150, v126, v126
	v_fmac_f32_e32 v151, v128, v128
	v_add_f32_e32 v152, v150, v151
	v_add_f32_e32 v163, v163, v152
	v_cvt_pk_f16_f32 v184, v126, v127
	v_cvt_pk_f16_f32 v185, v128, v129
	global_store_dwordx2 v147, v[178:179], s[10:11]
	global_store_dwordx2 v147, v[180:181], s[10:11] offset:512
	global_store_dwordx2 v147, v[182:183], s[10:11] offset:1024
	global_store_dwordx2 v147, v[184:185], s[10:11] offset:1536
	ds_bpermute_b32 v164, v130, v160
	ds_bpermute_b32 v165, v130, v161
	ds_bpermute_b32 v166, v130, v162
	ds_bpermute_b32 v167, v130, v163
	s_waitcnt lgkmcnt(0)
	v_add_f32_e32 v160, v160, v164
	v_add_f32_e32 v161, v161, v165
	v_add_f32_e32 v162, v162, v166
	v_add_f32_e32 v163, v163, v167
	ds_bpermute_b32 v164, v131, v160
	ds_bpermute_b32 v165, v131, v161
	ds_bpermute_b32 v166, v131, v162
	ds_bpermute_b32 v167, v131, v163
	s_waitcnt lgkmcnt(0)
	v_add_f32_e32 v160, v160, v164
	v_add_f32_e32 v161, v161, v165
	v_add_f32_e32 v162, v162, v166
	v_add_f32_e32 v163, v163, v167
	ds_bpermute_b32 v164, v132, v160
	ds_bpermute_b32 v165, v132, v161
	ds_bpermute_b32 v166, v132, v162
	ds_bpermute_b32 v167, v132, v163
	s_waitcnt lgkmcnt(0)
	v_add_f32_e32 v160, v160, v164
	v_add_f32_e32 v161, v161, v165
	v_add_f32_e32 v162, v162, v166
	v_add_f32_e32 v163, v163, v167
	ds_bpermute_b32 v164, v133, v160
	ds_bpermute_b32 v165, v133, v161
	ds_bpermute_b32 v166, v133, v162
	ds_bpermute_b32 v167, v133, v163
	s_waitcnt lgkmcnt(0)
	v_add_f32_e32 v160, v160, v164
	v_add_f32_e32 v161, v161, v165
	v_add_f32_e32 v162, v162, v166
	v_add_f32_e32 v163, v163, v167
	ds_bpermute_b32 v164, v134, v160
	ds_bpermute_b32 v165, v134, v161
	ds_bpermute_b32 v166, v134, v162
	ds_bpermute_b32 v167, v134, v163
	s_waitcnt lgkmcnt(0)
	v_add_f32_e32 v160, v160, v164
	v_add_f32_e32 v161, v161, v165
	v_add_f32_e32 v162, v162, v166
	v_add_f32_e32 v163, v163, v167
	ds_bpermute_b32 v164, v135, v160
	ds_bpermute_b32 v165, v135, v161
	ds_bpermute_b32 v166, v135, v162
	ds_bpermute_b32 v167, v135, v163
	s_waitcnt lgkmcnt(0)
	v_add_f32_e32 v160, v160, v164
	v_add_f32_e32 v161, v161, v165
	v_add_f32_e32 v162, v162, v166
	v_add_f32_e32 v163, v163, v167
	v_cndmask_b32_e64 v164, 0, v160, s[12:13]
	v_cndmask_b32_e64 v165, 0, v161, s[12:13]
	v_cndmask_b32_e64 v166, 0, v162, s[12:13]
	v_cndmask_b32_e64 v167, 0, v163, s[12:13]
	s_mov_b64 exec, 0xffff
	global_store_dword v186, v164, s[6:7]
	global_store_dword v187, v165, s[6:7]
	global_store_dword v188, v166, s[6:7]
	global_store_dword v189, v167, s[6:7]
	s_mov_b64 exec, -1
	s_branch .LBB0_37

; __device__ void p0_xconv(const Args& a) {
;     f16* XH = (f16*)(a.ws + WS_XH); float* SS = (float*)(a.ws + WS_SS);
;     int tid_ = threadIdx.x; asm volatile("" : "+v"(tid_));
;     const int lane = tid_ & 63, wv = tid_ >> 6;
;     const int nwv = (int)gridDim.x * 8;
;     for (int row0 = (int)blockIdx.x * 8 + wv; row0 < MROWS; row0 += 4 * nwv) {
;         f32x4 v[4][4];
; #pragma unroll
;         for (int r = 0; r < 4; ++r) {
;             const int row = row0 + r * nwv;
;             if (row < MROWS) {
;                 const float* src = (row < ROWS_PROMPT) ? a.x_prompt + (size_t)row * DM : a.x_sample + (size_t)(row - ROWS_PROMPT) * DM;
; #pragma unroll
;                 for (int i = 0; i < 4; ++i) v[r][i] = __builtin_nontemporal_load((const f32x4*)(src + i * 256 + lane * 4));
;             }
;         }
;     ...
;                 for (int o = 1; o < 64; o <<= 1) ss += __shfl_xor(ss, o);
;                 if (lane < 16) SS[(size_t)row * 16 + lane] = (lane == 0) ? ss : 0.f;
.LBB0_91:
	v_mov_b32_e32 v1, v0
	s_barrier
	s_mov_b32 s3, 0xc000
	v_ashrrev_i32_e32 v2, 6, v1
	v_lshl_add_u32 v78, s2, 3, v2
	v_add_u32_e32 v78, 0xa000, v78
	v_cmp_gt_i32_e32 vcc, s3, v78
	s_and_saveexec_b64 s[20:21], vcc
	s_cbranch_execz .LBB0_111
	v_and_b32_e32 v1, 63, v1
	v_mov_b32_e32 v67, 0
	v_lshlrev_b32_e32 v66, 2, v1
	v_lshlrev_b32_e32 v2, 3, v1
	v_mov_b32_e32 v3, v67
	s_load_dword s36, s[4:5], 0x0
	v_lshl_add_u64 v[68:69], s[40:41], 0, v[2:3]
	v_lshl_add_u64 v[2:3], s[40:41], 0, v[66:67]
	s_mov_b64 s[4:5], 0x1f800000
	v_cmp_gt_u32_e32 vcc, 16, v1
	v_lshl_add_u64 v[70:71], v[2:3], 0, s[4:5]
	v_cmp_eq_u32_e64 s[4:5], 0, v1
	v_mbcnt_lo_u32_b32 v1, -1, 0
	v_mbcnt_hi_u32_b32 v2, -1, v1
	v_and_b32_e32 v1, 64, v2
	v_add_u32_e32 v3, 64, v1
	v_xor_b32_e32 v1, 1, v2
	v_cmp_lt_i32_e64 s[6:7], v1, v3
	v_xor_b32_e32 v4, 2, v2
	s_waitcnt lgkmcnt(0)
	s_lshl_b32 s9, s36, 3
	v_cndmask_b32_e64 v1, v2, v1, s[6:7]
	v_cmp_lt_i32_e64 s[6:7], v4, v3
	s_add_i32 s44, s9, s9
	v_lshlrev_b32_e32 v1, 2, v1
	v_cndmask_b32_e64 v4, v2, v4, s[6:7]
	v_lshlrev_b32_e32 v80, 2, v4
	v_xor_b32_e32 v4, 4, v2
	v_cmp_lt_i32_e64 s[6:7], v4, v3
	s_lshl_b32 s33, s36, 4
	s_mul_i32 s36, s36, 24
	v_cndmask_b32_e64 v4, v2, v4, s[6:7]
	v_lshlrev_b32_e32 v81, 2, v4
	v_xor_b32_e32 v4, 8, v2
	v_cmp_lt_i32_e64 s[6:7], v4, v3
	s_mov_b64 s[22:23], 0
	s_movk_i32 s37, 0x4000
	v_cndmask_b32_e64 v4, v2, v4, s[6:7]
	v_lshlrev_b32_e32 v82, 2, v4
	v_xor_b32_e32 v4, 16, v2
	v_cmp_lt_i32_e64 s[6:7], v4, v3
	v_mov_b32_e32 v85, s19
	v_mov_b32_e32 v86, s17
	v_cndmask_b32_e64 v4, v2, v4, s[6:7]
	v_lshlrev_b32_e32 v83, 2, v4
	v_xor_b32_e32 v4, 32, v2
	v_cmp_lt_i32_e64 s[6:7], v4, v3
	v_mov_b32_e32 v87, s18
	v_mov_b32_e32 v88, s16
	v_cndmask_b32_e64 v2, v2, v4, s[6:7]
	v_lshlrev_b32_e32 v84, 2, v2
	v_lshlrev_b32_e32 v66, 2, v66
	s_add_i32 s44, s44, s9
	s_mov_b32 s45, 0xbfff
	s_branch .LBB0_94
